# v009 plus: GEMM load segments order m0 write, address add, LDS-DMA so the add supplies the m0 wait state and 46 s_nop 0 go
# baseline (speedup 1.0000x reference)
.LBB0_183:
	s_add_i32 s53, 0, 0x10000
	v_add_u32_e32 v142, s53, v147
	s_add_i32 s67, 0, 0x14000
	ds_read_b128 v[150:153], v142
	ds_read_b128 v[154:157], v142 offset:1024
	ds_read_b128 v[158:161], v142 offset:2048
	ds_read_b128 v[162:165], v142 offset:3072
	v_add_u32_e32 v142, s67, v147
	ds_read_b128 v[166:169], v142
	ds_read_b128 v[170:173], v142 offset:1024
	ds_read_b128 v[174:177], v142 offset:2048
	ds_read_b128 v[178:181], v142 offset:3072
	v_lshl_add_u64 v[144:145], s[4:5], 0, v[140:141]
	s_add_i32 m0, s59, 0xc000
	ds_read_b128 v[182:185], v149
	ds_read_b128 v[186:189], v149 offset:1024
	ds_read_b128 v[190:193], v149 offset:2048
	ds_read_b128 v[202:205], v149 offset:3072
	ds_read_b128 v[206:209], v149 offset:4096
	ds_read_b128 v[210:213], v149 offset:5120
	ds_read_b128 v[214:217], v149 offset:6144
	ds_read_b128 v[218:221], v149 offset:7168
	s_add_u32 s14, s4, 0xfffc0080
	s_addc_u32 s15, s5, -1
	s_cmp_eq_u32 s49, 12
	s_cselect_b32 s55, s21, s15
	s_cselect_b32 s54, s28, s14
	s_cselect_b32 s15, s29, s47
	s_cselect_b32 s14, s33, s37
	global_load_lds_dwordx4 v[144:145], off
	s_add_i32 m0, s59, 0xe000
	v_lshl_add_u64 v[144:145], s[4:5], 0, v[138:139]
	global_load_lds_dwordx4 v[144:145], off
	s_waitcnt vmcnt(8)
	s_waitcnt lgkmcnt(0)
	s_setprio 1
	s_barrier
	v_mfma_f32_16x16x32_bf16 v[126:129], v[150:153], v[182:185], v[126:129]
	v_mfma_f32_16x16x32_bf16 v[122:125], v[158:161], v[182:185], v[122:125]
	v_mfma_f32_16x16x32_bf16 v[110:113], v[150:153], v[190:193], v[110:113]
	v_mfma_f32_16x16x32_bf16 v[106:109], v[158:161], v[190:193], v[106:109]
	v_mfma_f32_16x16x32_bf16 v[94:97], v[150:153], v[206:209], v[94:97]
	v_mfma_f32_16x16x32_bf16 v[90:93], v[158:161], v[206:209], v[90:93]
	v_mfma_f32_16x16x32_bf16 v[78:81], v[150:153], v[214:217], v[78:81]
	v_mfma_f32_16x16x32_bf16 v[74:77], v[158:161], v[214:217], v[74:77]
	v_mfma_f32_16x16x32_bf16 v[126:129], v[154:157], v[186:189], v[126:129]
	v_mfma_f32_16x16x32_bf16 v[122:125], v[162:165], v[186:189], v[122:125]
	v_mfma_f32_16x16x32_bf16 v[110:113], v[154:157], v[202:205], v[110:113]
	v_mfma_f32_16x16x32_bf16 v[106:109], v[162:165], v[202:205], v[106:109]
	v_mfma_f32_16x16x32_bf16 v[94:97], v[154:157], v[210:213], v[94:97]
	v_mfma_f32_16x16x32_bf16 v[90:93], v[162:165], v[210:213], v[90:93]
	v_mfma_f32_16x16x32_bf16 v[78:81], v[154:157], v[218:221], v[78:81]
	v_mfma_f32_16x16x32_bf16 v[74:77], v[162:165], v[218:221], v[74:77]
	v_mfma_f32_16x16x32_bf16 v[118:121], v[166:169], v[182:185], v[118:121]
	v_mfma_f32_16x16x32_bf16 v[114:117], v[174:177], v[182:185], v[114:117]
	v_mfma_f32_16x16x32_bf16 v[102:105], v[166:169], v[190:193], v[102:105]
	v_mfma_f32_16x16x32_bf16 v[98:101], v[174:177], v[190:193], v[98:101]
	v_mfma_f32_16x16x32_bf16 v[86:89], v[166:169], v[206:209], v[86:89]
	v_mfma_f32_16x16x32_bf16 v[82:85], v[174:177], v[206:209], v[82:85]
	v_mfma_f32_16x16x32_bf16 v[70:73], v[166:169], v[214:217], v[70:73]
	v_mfma_f32_16x16x32_bf16 v[66:69], v[174:177], v[214:217], v[66:69]
	v_mfma_f32_16x16x32_bf16 v[118:121], v[170:173], v[186:189], v[118:121]
	v_mfma_f32_16x16x32_bf16 v[114:117], v[178:181], v[186:189], v[114:117]
	v_mfma_f32_16x16x32_bf16 v[102:105], v[170:173], v[202:205], v[102:105]
	v_mfma_f32_16x16x32_bf16 v[98:101], v[178:181], v[202:205], v[98:101]
	v_mfma_f32_16x16x32_bf16 v[86:89], v[170:173], v[210:213], v[86:89]
	v_mfma_f32_16x16x32_bf16 v[82:85], v[178:181], v[210:213], v[82:85]
	v_mfma_f32_16x16x32_bf16 v[70:73], v[170:173], v[218:221], v[70:73]
	v_mfma_f32_16x16x32_bf16 v[66:69], v[178:181], v[218:221], v[66:69]
	s_barrier
	s_setprio 0
	s_add_i32 s53, s53, s58
	v_lshl_add_u64 v[144:145], s[14:15], 0, v[134:135]
	s_mov_b32 m0, s53
	ds_read_b128 v[182:185], v149 offset:16384
	ds_read_b128 v[186:189], v149 offset:17408
	ds_read_b128 v[190:193], v149 offset:18432
	ds_read_b128 v[202:205], v149 offset:19456
	ds_read_b128 v[206:209], v149 offset:20480
	ds_read_b128 v[210:213], v149 offset:21504
	ds_read_b128 v[214:217], v149 offset:22528
	ds_read_b128 v[218:221], v149 offset:23552
	global_load_lds_dwordx4 v[144:145], off
	s_add_i32 m0, s53, 0x2000
	s_add_u32 s68, s14, 0x40000
	v_lshl_add_u64 v[222:223], s[14:15], 0, v[130:131]
	s_addc_u32 s69, s15, 0
	s_add_i32 s53, s67, s58
	global_load_lds_dwordx4 v[222:223], off
	v_lshl_add_u64 v[232:233], s[68:69], 0, v[134:135]
	s_mov_b32 m0, s53
	v_lshl_add_u64 v[234:235], s[54:55], 0, v[132:133]
	global_load_lds_dwordx4 v[232:233], off
	s_add_i32 m0, s53, 0x2000
	v_lshl_add_u64 v[232:233], s[68:69], 0, v[130:131]
	global_load_lds_dwordx4 v[232:233], off
	s_mov_b32 m0, s59
	v_lshl_add_u64 v[232:233], s[54:55], 0, v[136:137]
	global_load_lds_dwordx4 v[232:233], off
	s_mov_b32 m0, s60
	s_nop 0
	global_load_lds_dwordx4 v[234:235], off
	s_waitcnt vmcnt(8)
	s_waitcnt lgkmcnt(0)
	s_setprio 1
	s_barrier
	v_mfma_f32_16x16x32_bf16 v[62:65], v[150:153], v[182:185], v[62:65]
	v_mfma_f32_16x16x32_bf16 v[58:61], v[158:161], v[182:185], v[58:61]
	v_mfma_f32_16x16x32_bf16 v[50:53], v[150:153], v[190:193], v[50:53]
	v_mfma_f32_16x16x32_bf16 v[42:45], v[158:161], v[190:193], v[42:45]
	v_mfma_f32_16x16x32_bf16 v[34:37], v[150:153], v[206:209], v[34:37]
	v_mfma_f32_16x16x32_bf16 v[26:29], v[158:161], v[206:209], v[26:29]
	v_mfma_f32_16x16x32_bf16 v[18:21], v[150:153], v[214:217], v[18:21]
	v_mfma_f32_16x16x32_bf16 v[10:13], v[158:161], v[214:217], v[10:13]
	v_mfma_f32_16x16x32_bf16 v[62:65], v[154:157], v[186:189], v[62:65]
	v_mfma_f32_16x16x32_bf16 v[58:61], v[162:165], v[186:189], v[58:61]
	v_mfma_f32_16x16x32_bf16 v[50:53], v[154:157], v[202:205], v[50:53]
	v_mfma_f32_16x16x32_bf16 v[42:45], v[162:165], v[202:205], v[42:45]
	v_mfma_f32_16x16x32_bf16 v[34:37], v[154:157], v[210:213], v[34:37]
	v_mfma_f32_16x16x32_bf16 v[26:29], v[162:165], v[210:213], v[26:29]
	v_mfma_f32_16x16x32_bf16 v[18:21], v[154:157], v[218:221], v[18:21]
	v_mfma_f32_16x16x32_bf16 v[10:13], v[162:165], v[218:221], v[10:13]
	v_mfma_f32_16x16x32_bf16 v[54:57], v[166:169], v[182:185], v[54:57]
	v_mfma_f32_16x16x32_bf16 v[46:49], v[174:177], v[182:185], v[46:49]
	v_mfma_f32_16x16x32_bf16 v[38:41], v[166:169], v[190:193], v[38:41]
	v_mfma_f32_16x16x32_bf16 v[30:33], v[174:177], v[190:193], v[30:33]
	v_mfma_f32_16x16x32_bf16 v[22:25], v[166:169], v[206:209], v[22:25]
	v_mfma_f32_16x16x32_bf16 v[14:17], v[174:177], v[206:209], v[14:17]
	v_mfma_f32_16x16x32_bf16 v[6:9], v[166:169], v[214:217], v[6:9]
	v_mfma_f32_16x16x32_bf16 v[2:5], v[174:177], v[214:217], v[2:5]
	v_mfma_f32_16x16x32_bf16 v[54:57], v[170:173], v[186:189], v[54:57]
	v_mfma_f32_16x16x32_bf16 v[46:49], v[178:181], v[186:189], v[46:49]
	v_mfma_f32_16x16x32_bf16 v[38:41], v[170:173], v[202:205], v[38:41]
	v_mfma_f32_16x16x32_bf16 v[30:33], v[178:181], v[202:205], v[30:33]
	v_mfma_f32_16x16x32_bf16 v[22:25], v[170:173], v[210:213], v[22:25]
	v_mfma_f32_16x16x32_bf16 v[14:17], v[178:181], v[210:213], v[14:17]
	v_mfma_f32_16x16x32_bf16 v[6:9], v[170:173], v[218:221], v[6:9]
	v_mfma_f32_16x16x32_bf16 v[2:5], v[178:181], v[218:221], v[2:5]
	s_barrier
	s_setprio 0
	s_add_i32 s53, 0, 0x18000
	v_add_u32_e32 v142, s53, v147
	s_add_i32 s67, 0, 0x1c000
	ds_read_b128 v[150:153], v142
	ds_read_b128 v[154:157], v142 offset:1024
	ds_read_b128 v[158:161], v142 offset:2048
	ds_read_b128 v[162:165], v142 offset:3072
	v_add_u32_e32 v142, s67, v147
	ds_read_b128 v[166:169], v142
	ds_read_b128 v[170:173], v142 offset:1024
	ds_read_b128 v[174:177], v142 offset:2048
	ds_read_b128 v[178:181], v142 offset:3072
	s_add_u32 s54, s54, 0x40000
	s_addc_u32 s55, s55, 0
	s_mov_b32 m0, s61
	v_lshl_add_u64 v[236:237], s[54:55], 0, v[136:137]
	ds_read_b128 v[182:185], v149 offset:32768
	ds_read_b128 v[186:189], v149 offset:33792
	ds_read_b128 v[190:193], v149 offset:34816
	ds_read_b128 v[202:205], v149 offset:35840
	ds_read_b128 v[206:209], v149 offset:36864
	ds_read_b128 v[210:213], v149 offset:37888
	ds_read_b128 v[214:217], v149 offset:38912
	ds_read_b128 v[218:221], v149 offset:39936
	global_load_lds_dwordx4 v[236:237], off
	s_mov_b32 m0, s62
	v_lshl_add_u64 v[236:237], s[54:55], 0, v[132:133]
	global_load_lds_dwordx4 v[236:237], off
	s_waitcnt vmcnt(8)
	s_waitcnt lgkmcnt(0)
	s_setprio 1
	s_barrier
	v_mfma_f32_16x16x32_bf16 v[126:129], v[150:153], v[182:185], v[126:129]
	v_mfma_f32_16x16x32_bf16 v[122:125], v[158:161], v[182:185], v[122:125]
	v_mfma_f32_16x16x32_bf16 v[110:113], v[150:153], v[190:193], v[110:113]
	v_mfma_f32_16x16x32_bf16 v[106:109], v[158:161], v[190:193], v[106:109]
	v_mfma_f32_16x16x32_bf16 v[94:97], v[150:153], v[206:209], v[94:97]
	v_mfma_f32_16x16x32_bf16 v[90:93], v[158:161], v[206:209], v[90:93]
	v_mfma_f32_16x16x32_bf16 v[78:81], v[150:153], v[214:217], v[78:81]
	v_mfma_f32_16x16x32_bf16 v[74:77], v[158:161], v[214:217], v[74:77]
	v_mfma_f32_16x16x32_bf16 v[126:129], v[154:157], v[186:189], v[126:129]
	v_mfma_f32_16x16x32_bf16 v[122:125], v[162:165], v[186:189], v[122:125]
	v_mfma_f32_16x16x32_bf16 v[110:113], v[154:157], v[202:205], v[110:113]
	v_mfma_f32_16x16x32_bf16 v[106:109], v[162:165], v[202:205], v[106:109]
	v_mfma_f32_16x16x32_bf16 v[94:97], v[154:157], v[210:213], v[94:97]
	v_mfma_f32_16x16x32_bf16 v[90:93], v[162:165], v[210:213], v[90:93]
	v_mfma_f32_16x16x32_bf16 v[78:81], v[154:157], v[218:221], v[78:81]
	v_mfma_f32_16x16x32_bf16 v[74:77], v[162:165], v[218:221], v[74:77]
	v_mfma_f32_16x16x32_bf16 v[118:121], v[166:169], v[182:185], v[118:121]
	v_mfma_f32_16x16x32_bf16 v[114:117], v[174:177], v[182:185], v[114:117]
	v_mfma_f32_16x16x32_bf16 v[102:105], v[166:169], v[190:193], v[102:105]
	v_mfma_f32_16x16x32_bf16 v[98:101], v[174:177], v[190:193], v[98:101]
	v_mfma_f32_16x16x32_bf16 v[86:89], v[166:169], v[206:209], v[86:89]
	v_mfma_f32_16x16x32_bf16 v[82:85], v[174:177], v[206:209], v[82:85]
	v_mfma_f32_16x16x32_bf16 v[70:73], v[166:169], v[214:217], v[70:73]
	v_mfma_f32_16x16x32_bf16 v[66:69], v[174:177], v[214:217], v[66:69]
	v_mfma_f32_16x16x32_bf16 v[118:121], v[170:173], v[186:189], v[118:121]
	v_mfma_f32_16x16x32_bf16 v[114:117], v[178:181], v[186:189], v[114:117]
	v_mfma_f32_16x16x32_bf16 v[102:105], v[170:173], v[202:205], v[102:105]
	v_mfma_f32_16x16x32_bf16 v[98:101], v[178:181], v[202:205], v[98:101]
	v_mfma_f32_16x16x32_bf16 v[86:89], v[170:173], v[210:213], v[86:89]
	v_mfma_f32_16x16x32_bf16 v[82:85], v[178:181], v[210:213], v[82:85]
	v_mfma_f32_16x16x32_bf16 v[70:73], v[170:173], v[218:221], v[70:73]
	v_mfma_f32_16x16x32_bf16 v[66:69], v[178:181], v[218:221], v[66:69]
	s_barrier
	s_setprio 0
	s_add_i32 s53, s53, s58
	v_lshl_add_u64 v[144:145], v[144:145], 0, s[10:11]
	s_mov_b32 m0, s53
	ds_read_b128 v[182:185], v149 offset:49152
	ds_read_b128 v[186:189], v149 offset:50176
	ds_read_b128 v[190:193], v149 offset:51200
	ds_read_b128 v[202:205], v149 offset:52224
	ds_read_b128 v[206:209], v149 offset:53248
	ds_read_b128 v[210:213], v149 offset:54272
	ds_read_b128 v[214:217], v149 offset:55296
	ds_read_b128 v[218:221], v149 offset:56320
	s_add_i32 s49, s49, 2
	s_add_u32 s37, s37, 0x100
	s_addc_u32 s47, s47, 0
	s_add_u32 s4, s4, 0x100
	s_addc_u32 s5, s5, 0
	global_load_lds_dwordx4 v[144:145], off
	s_add_i32 m0, s53, 0x2000
	s_add_u32 s14, s14, 0x40080
	v_lshl_add_u64 v[144:145], v[222:223], 0, s[10:11]
	s_addc_u32 s15, s15, 0
	s_add_i32 s53, s67, s58
	global_load_lds_dwordx4 v[144:145], off
	s_mov_b32 m0, s53
	v_lshl_add_u64 v[144:145], s[14:15], 0, v[134:135]
	global_load_lds_dwordx4 v[144:145], off
	s_add_i32 m0, s53, 0x2000
	v_lshl_add_u64 v[144:145], s[14:15], 0, v[130:131]
	global_load_lds_dwordx4 v[144:145], off
	s_mov_b32 m0, s65
	v_lshl_add_u64 v[144:145], v[232:233], 0, s[10:11]
	global_load_lds_dwordx4 v[144:145], off
	s_mov_b32 m0, s66
	v_lshl_add_u64 v[144:145], v[234:235], 0, s[10:11]
	global_load_lds_dwordx4 v[144:145], off
	s_waitcnt vmcnt(8)
	s_waitcnt lgkmcnt(0)
	s_setprio 1
	s_barrier
	v_mfma_f32_16x16x32_bf16 v[62:65], v[150:153], v[182:185], v[62:65]
	v_mfma_f32_16x16x32_bf16 v[58:61], v[158:161], v[182:185], v[58:61]
	v_mfma_f32_16x16x32_bf16 v[50:53], v[150:153], v[190:193], v[50:53]
	v_mfma_f32_16x16x32_bf16 v[42:45], v[158:161], v[190:193], v[42:45]
	v_mfma_f32_16x16x32_bf16 v[34:37], v[150:153], v[206:209], v[34:37]
	v_mfma_f32_16x16x32_bf16 v[26:29], v[158:161], v[206:209], v[26:29]
	v_mfma_f32_16x16x32_bf16 v[18:21], v[150:153], v[214:217], v[18:21]
	v_mfma_f32_16x16x32_bf16 v[10:13], v[158:161], v[214:217], v[10:13]
	v_mfma_f32_16x16x32_bf16 v[62:65], v[154:157], v[186:189], v[62:65]
	v_mfma_f32_16x16x32_bf16 v[58:61], v[162:165], v[186:189], v[58:61]
	v_mfma_f32_16x16x32_bf16 v[50:53], v[154:157], v[202:205], v[50:53]
	v_mfma_f32_16x16x32_bf16 v[42:45], v[162:165], v[202:205], v[42:45]
	v_mfma_f32_16x16x32_bf16 v[34:37], v[154:157], v[210:213], v[34:37]
	v_mfma_f32_16x16x32_bf16 v[26:29], v[162:165], v[210:213], v[26:29]
	v_mfma_f32_16x16x32_bf16 v[18:21], v[154:157], v[218:221], v[18:21]
	v_mfma_f32_16x16x32_bf16 v[10:13], v[162:165], v[218:221], v[10:13]
	v_mfma_f32_16x16x32_bf16 v[54:57], v[166:169], v[182:185], v[54:57]
	v_mfma_f32_16x16x32_bf16 v[46:49], v[174:177], v[182:185], v[46:49]
	v_mfma_f32_16x16x32_bf16 v[38:41], v[166:169], v[190:193], v[38:41]
	v_mfma_f32_16x16x32_bf16 v[30:33], v[174:177], v[190:193], v[30:33]
	v_mfma_f32_16x16x32_bf16 v[22:25], v[166:169], v[206:209], v[22:25]
	v_mfma_f32_16x16x32_bf16 v[14:17], v[174:177], v[206:209], v[14:17]
	v_mfma_f32_16x16x32_bf16 v[6:9], v[166:169], v[214:217], v[6:9]
	v_mfma_f32_16x16x32_bf16 v[2:5], v[174:177], v[214:217], v[2:5]
	v_mfma_f32_16x16x32_bf16 v[54:57], v[170:173], v[186:189], v[54:57]
	v_mfma_f32_16x16x32_bf16 v[46:49], v[178:181], v[186:189], v[46:49]
	v_mfma_f32_16x16x32_bf16 v[38:41], v[170:173], v[202:205], v[38:41]
	v_mfma_f32_16x16x32_bf16 v[30:33], v[178:181], v[202:205], v[30:33]
	v_mfma_f32_16x16x32_bf16 v[22:25], v[170:173], v[210:213], v[22:25]
	v_mfma_f32_16x16x32_bf16 v[14:17], v[178:181], v[210:213], v[14:17]
	v_mfma_f32_16x16x32_bf16 v[6:9], v[170:173], v[218:221], v[6:9]
	v_mfma_f32_16x16x32_bf16 v[2:5], v[178:181], v[218:221], v[2:5]
	s_barrier
	s_setprio 0
	s_cmp_gt_u32 s49, 13
	s_cbranch_scc0 .LBB0_183
	s_and_b64 vcc, exec, s[44:45]
	s_cbranch_vccz .LBB0_186
	s_barrier

.LBB0_481:
	s_add_i32 s70, 0, 0x10000
	s_add_i32 s72, 0, 0x14000
	v_add_u32_e32 v134, s70, v183
	v_add_u32_e32 v168, s72, v183
	ds_read_b128 v[114:117], v134
	ds_read_b128 v[118:121], v134 offset:1024
	ds_read_b128 v[122:125], v134 offset:2048
	ds_read_b128 v[134:137], v134 offset:3072
	ds_read_b128 v[146:149], v168
	ds_read_b128 v[150:153], v168 offset:1024
	ds_read_b128 v[164:167], v168 offset:2048
	ds_read_b128 v[168:171], v168 offset:3072
	v_lshl_add_u64 v[180:181], s[12:13], 0, v[162:163]
	s_add_i32 m0, s63, 0xc000
	ds_read_b128 v[172:175], v185
	ds_read_b128 v[176:179], v185 offset:1024
	ds_read_b128 v[186:189], v185 offset:2048
	ds_read_b128 v[190:193], v185 offset:3072
	ds_read_b128 v[202:205], v185 offset:4096
	ds_read_b128 v[206:209], v185 offset:5120
	ds_read_b128 v[210:213], v185 offset:6144
	ds_read_b128 v[214:217], v185 offset:7168
	s_add_u32 s14, s12, 0xfffc0080
	s_addc_u32 s15, s13, -1
	s_cmp_eq_u32 s53, 12
	s_cselect_b32 s59, s28, s15
	s_cselect_b32 s58, s29, s14
	s_cselect_b32 s15, s33, s51
	s_cselect_b32 s14, s36, s37
	global_load_lds_dwordx4 v[180:181], off
	s_add_i32 m0, s63, 0xe000
	v_lshl_add_u64 v[180:181], s[12:13], 0, v[160:161]
	global_load_lds_dwordx4 v[180:181], off
	s_waitcnt vmcnt(8)
	s_waitcnt lgkmcnt(0)
	s_setprio 1
	s_barrier
	v_mfma_f32_16x16x32_bf16 v[142:145], v[114:117], v[172:175], v[142:145]
	v_mfma_f32_16x16x32_bf16 v[138:141], v[122:125], v[172:175], v[138:141]
	v_mfma_f32_16x16x32_bf16 v[110:113], v[114:117], v[186:189], v[110:113]
	v_mfma_f32_16x16x32_bf16 v[106:109], v[122:125], v[186:189], v[106:109]
	v_mfma_f32_16x16x32_bf16 v[94:97], v[114:117], v[202:205], v[94:97]
	v_mfma_f32_16x16x32_bf16 v[90:93], v[122:125], v[202:205], v[90:93]
	v_mfma_f32_16x16x32_bf16 v[78:81], v[114:117], v[210:213], v[78:81]
	v_mfma_f32_16x16x32_bf16 v[74:77], v[122:125], v[210:213], v[74:77]
	v_mfma_f32_16x16x32_bf16 v[142:145], v[118:121], v[176:179], v[142:145]
	v_mfma_f32_16x16x32_bf16 v[138:141], v[134:137], v[176:179], v[138:141]
	v_mfma_f32_16x16x32_bf16 v[110:113], v[118:121], v[190:193], v[110:113]
	v_mfma_f32_16x16x32_bf16 v[106:109], v[134:137], v[190:193], v[106:109]
	v_mfma_f32_16x16x32_bf16 v[94:97], v[118:121], v[206:209], v[94:97]
	v_mfma_f32_16x16x32_bf16 v[90:93], v[134:137], v[206:209], v[90:93]
	v_mfma_f32_16x16x32_bf16 v[78:81], v[118:121], v[214:217], v[78:81]
	v_mfma_f32_16x16x32_bf16 v[74:77], v[134:137], v[214:217], v[74:77]
	v_mfma_f32_16x16x32_bf16 v[130:133], v[146:149], v[172:175], v[130:133]
	v_mfma_f32_16x16x32_bf16 v[126:129], v[164:167], v[172:175], v[126:129]
	v_mfma_f32_16x16x32_bf16 v[102:105], v[146:149], v[186:189], v[102:105]
	v_mfma_f32_16x16x32_bf16 v[98:101], v[164:167], v[186:189], v[98:101]
	v_mfma_f32_16x16x32_bf16 v[86:89], v[146:149], v[202:205], v[86:89]
	v_mfma_f32_16x16x32_bf16 v[82:85], v[164:167], v[202:205], v[82:85]
	v_mfma_f32_16x16x32_bf16 v[70:73], v[146:149], v[210:213], v[70:73]
	v_mfma_f32_16x16x32_bf16 v[66:69], v[164:167], v[210:213], v[66:69]
	v_mfma_f32_16x16x32_bf16 v[130:133], v[150:153], v[176:179], v[130:133]
	v_mfma_f32_16x16x32_bf16 v[126:129], v[168:171], v[176:179], v[126:129]
	v_mfma_f32_16x16x32_bf16 v[102:105], v[150:153], v[190:193], v[102:105]
	v_mfma_f32_16x16x32_bf16 v[98:101], v[168:171], v[190:193], v[98:101]
	v_mfma_f32_16x16x32_bf16 v[86:89], v[150:153], v[206:209], v[86:89]
	v_mfma_f32_16x16x32_bf16 v[82:85], v[168:171], v[206:209], v[82:85]
	v_mfma_f32_16x16x32_bf16 v[70:73], v[150:153], v[214:217], v[70:73]
	v_mfma_f32_16x16x32_bf16 v[66:69], v[168:171], v[214:217], v[66:69]
	s_barrier
	s_setprio 0
	s_add_i32 s70, s70, s62
	v_lshl_add_u64 v[180:181], s[14:15], 0, v[0:1]
	s_mov_b32 m0, s70
	ds_read_b128 v[172:175], v185 offset:16384
	ds_read_b128 v[176:179], v185 offset:17408
	ds_read_b128 v[186:189], v185 offset:18432
	ds_read_b128 v[190:193], v185 offset:19456
	ds_read_b128 v[202:205], v185 offset:20480
	ds_read_b128 v[206:209], v185 offset:21504
	ds_read_b128 v[210:213], v185 offset:22528
	ds_read_b128 v[214:217], v185 offset:23552
	global_load_lds_dwordx4 v[180:181], off
	s_add_i32 m0, s70, 0x2000
	s_add_u32 s70, s14, 0x40000
	v_lshl_add_u64 v[218:219], s[14:15], 0, v[154:155]
	s_addc_u32 s71, s15, 0
	s_add_i32 s72, s72, s62
	global_load_lds_dwordx4 v[218:219], off
	v_lshl_add_u64 v[220:221], s[70:71], 0, v[0:1]
	s_mov_b32 m0, s72
	v_lshl_add_u64 v[222:223], s[58:59], 0, v[156:157]
	global_load_lds_dwordx4 v[220:221], off
	s_add_i32 m0, s72, 0x2000
	v_lshl_add_u64 v[220:221], s[70:71], 0, v[154:155]
	global_load_lds_dwordx4 v[220:221], off
	s_mov_b32 m0, s63
	v_lshl_add_u64 v[220:221], s[58:59], 0, v[158:159]
	global_load_lds_dwordx4 v[220:221], off
	s_mov_b32 m0, s64
	s_nop 0
	global_load_lds_dwordx4 v[222:223], off
	s_waitcnt vmcnt(8)
	s_waitcnt lgkmcnt(0)
	s_setprio 1
	s_barrier
	v_mfma_f32_16x16x32_bf16 v[62:65], v[114:117], v[172:175], v[62:65]
	v_mfma_f32_16x16x32_bf16 v[58:61], v[122:125], v[172:175], v[58:61]
	v_mfma_f32_16x16x32_bf16 v[46:49], v[114:117], v[186:189], v[46:49]
	v_mfma_f32_16x16x32_bf16 v[42:45], v[122:125], v[186:189], v[42:45]
	v_mfma_f32_16x16x32_bf16 v[30:33], v[114:117], v[202:205], v[30:33]
	v_mfma_f32_16x16x32_bf16 v[26:29], v[122:125], v[202:205], v[26:29]
	v_mfma_f32_16x16x32_bf16 v[14:17], v[114:117], v[210:213], v[14:17]
	v_mfma_f32_16x16x32_bf16 v[10:13], v[122:125], v[210:213], v[10:13]
	v_mfma_f32_16x16x32_bf16 v[62:65], v[118:121], v[176:179], v[62:65]
	v_mfma_f32_16x16x32_bf16 v[58:61], v[134:137], v[176:179], v[58:61]
	v_mfma_f32_16x16x32_bf16 v[46:49], v[118:121], v[190:193], v[46:49]
	v_mfma_f32_16x16x32_bf16 v[42:45], v[134:137], v[190:193], v[42:45]
	v_mfma_f32_16x16x32_bf16 v[30:33], v[118:121], v[206:209], v[30:33]
	v_mfma_f32_16x16x32_bf16 v[26:29], v[134:137], v[206:209], v[26:29]
	v_mfma_f32_16x16x32_bf16 v[14:17], v[118:121], v[214:217], v[14:17]
	v_mfma_f32_16x16x32_bf16 v[10:13], v[134:137], v[214:217], v[10:13]
	v_mfma_f32_16x16x32_bf16 v[54:57], v[146:149], v[172:175], v[54:57]
	v_mfma_f32_16x16x32_bf16 v[50:53], v[164:167], v[172:175], v[50:53]
	v_mfma_f32_16x16x32_bf16 v[38:41], v[146:149], v[186:189], v[38:41]
	v_mfma_f32_16x16x32_bf16 v[34:37], v[164:167], v[186:189], v[34:37]
	v_mfma_f32_16x16x32_bf16 v[22:25], v[146:149], v[202:205], v[22:25]
	v_mfma_f32_16x16x32_bf16 v[18:21], v[164:167], v[202:205], v[18:21]
	v_mfma_f32_16x16x32_bf16 v[6:9], v[146:149], v[210:213], v[6:9]
	v_mfma_f32_16x16x32_bf16 v[2:5], v[164:167], v[210:213], v[2:5]
	v_mfma_f32_16x16x32_bf16 v[54:57], v[150:153], v[176:179], v[54:57]
	v_mfma_f32_16x16x32_bf16 v[50:53], v[168:171], v[176:179], v[50:53]
	v_mfma_f32_16x16x32_bf16 v[38:41], v[150:153], v[190:193], v[38:41]
	v_mfma_f32_16x16x32_bf16 v[34:37], v[168:171], v[190:193], v[34:37]
	v_mfma_f32_16x16x32_bf16 v[22:25], v[150:153], v[206:209], v[22:25]
	v_mfma_f32_16x16x32_bf16 v[18:21], v[168:171], v[206:209], v[18:21]
	v_mfma_f32_16x16x32_bf16 v[6:9], v[150:153], v[214:217], v[6:9]
	v_mfma_f32_16x16x32_bf16 v[2:5], v[168:171], v[214:217], v[2:5]
	s_barrier
	s_setprio 0
	s_add_i32 s70, 0, 0x18000
	s_add_i32 s71, 0, 0x1c000
	v_add_u32_e32 v134, s70, v183
	v_add_u32_e32 v168, s71, v183
	ds_read_b128 v[114:117], v134
	ds_read_b128 v[118:121], v134 offset:1024
	ds_read_b128 v[122:125], v134 offset:2048
	ds_read_b128 v[134:137], v134 offset:3072
	ds_read_b128 v[146:149], v168
	ds_read_b128 v[150:153], v168 offset:1024
	ds_read_b128 v[164:167], v168 offset:2048
	ds_read_b128 v[168:171], v168 offset:3072
	s_add_u32 s58, s58, 0x40000
	s_addc_u32 s59, s59, 0
	s_mov_b32 m0, s65
	v_lshl_add_u64 v[232:233], s[58:59], 0, v[158:159]
	ds_read_b128 v[172:175], v185 offset:32768
	ds_read_b128 v[176:179], v185 offset:33792
	ds_read_b128 v[186:189], v185 offset:34816
	ds_read_b128 v[190:193], v185 offset:35840
	ds_read_b128 v[202:205], v185 offset:36864
	ds_read_b128 v[206:209], v185 offset:37888
	ds_read_b128 v[210:213], v185 offset:38912
	ds_read_b128 v[214:217], v185 offset:39936
	global_load_lds_dwordx4 v[232:233], off
	s_mov_b32 m0, s66
	v_lshl_add_u64 v[232:233], s[58:59], 0, v[156:157]
	global_load_lds_dwordx4 v[232:233], off
	s_waitcnt vmcnt(8)
	s_waitcnt lgkmcnt(0)
	s_setprio 1
	s_barrier
	v_mfma_f32_16x16x32_bf16 v[142:145], v[114:117], v[172:175], v[142:145]
	v_mfma_f32_16x16x32_bf16 v[138:141], v[122:125], v[172:175], v[138:141]
	v_mfma_f32_16x16x32_bf16 v[110:113], v[114:117], v[186:189], v[110:113]
	v_mfma_f32_16x16x32_bf16 v[106:109], v[122:125], v[186:189], v[106:109]
	v_mfma_f32_16x16x32_bf16 v[94:97], v[114:117], v[202:205], v[94:97]
	v_mfma_f32_16x16x32_bf16 v[90:93], v[122:125], v[202:205], v[90:93]
	v_mfma_f32_16x16x32_bf16 v[78:81], v[114:117], v[210:213], v[78:81]
	v_mfma_f32_16x16x32_bf16 v[74:77], v[122:125], v[210:213], v[74:77]
	v_mfma_f32_16x16x32_bf16 v[142:145], v[118:121], v[176:179], v[142:145]
	v_mfma_f32_16x16x32_bf16 v[138:141], v[134:137], v[176:179], v[138:141]
	v_mfma_f32_16x16x32_bf16 v[110:113], v[118:121], v[190:193], v[110:113]
	v_mfma_f32_16x16x32_bf16 v[106:109], v[134:137], v[190:193], v[106:109]
	v_mfma_f32_16x16x32_bf16 v[94:97], v[118:121], v[206:209], v[94:97]
	v_mfma_f32_16x16x32_bf16 v[90:93], v[134:137], v[206:209], v[90:93]
	v_mfma_f32_16x16x32_bf16 v[78:81], v[118:121], v[214:217], v[78:81]
	v_mfma_f32_16x16x32_bf16 v[74:77], v[134:137], v[214:217], v[74:77]
	v_mfma_f32_16x16x32_bf16 v[130:133], v[146:149], v[172:175], v[130:133]
	v_mfma_f32_16x16x32_bf16 v[126:129], v[164:167], v[172:175], v[126:129]
	v_mfma_f32_16x16x32_bf16 v[102:105], v[146:149], v[186:189], v[102:105]
	v_mfma_f32_16x16x32_bf16 v[98:101], v[164:167], v[186:189], v[98:101]
	v_mfma_f32_16x16x32_bf16 v[86:89], v[146:149], v[202:205], v[86:89]
	v_mfma_f32_16x16x32_bf16 v[82:85], v[164:167], v[202:205], v[82:85]
	v_mfma_f32_16x16x32_bf16 v[70:73], v[146:149], v[210:213], v[70:73]
	v_mfma_f32_16x16x32_bf16 v[66:69], v[164:167], v[210:213], v[66:69]
	v_mfma_f32_16x16x32_bf16 v[130:133], v[150:153], v[176:179], v[130:133]
	v_mfma_f32_16x16x32_bf16 v[126:129], v[168:171], v[176:179], v[126:129]
	v_mfma_f32_16x16x32_bf16 v[102:105], v[150:153], v[190:193], v[102:105]
	v_mfma_f32_16x16x32_bf16 v[98:101], v[168:171], v[190:193], v[98:101]
	v_mfma_f32_16x16x32_bf16 v[86:89], v[150:153], v[206:209], v[86:89]
	v_mfma_f32_16x16x32_bf16 v[82:85], v[168:171], v[206:209], v[82:85]
	v_mfma_f32_16x16x32_bf16 v[70:73], v[150:153], v[214:217], v[70:73]
	v_mfma_f32_16x16x32_bf16 v[66:69], v[168:171], v[214:217], v[66:69]
	s_barrier
	s_setprio 0
	s_add_i32 s58, s70, s62
	v_lshl_add_u64 v[180:181], v[180:181], 0, s[10:11]
	s_mov_b32 m0, s58
	ds_read_b128 v[172:175], v185 offset:49152
	ds_read_b128 v[176:179], v185 offset:50176
	ds_read_b128 v[186:189], v185 offset:51200
	ds_read_b128 v[190:193], v185 offset:52224
	ds_read_b128 v[202:205], v185 offset:53248
	ds_read_b128 v[206:209], v185 offset:54272
	ds_read_b128 v[210:213], v185 offset:55296
	ds_read_b128 v[214:217], v185 offset:56320
	s_add_i32 s53, s53, 2
	s_add_u32 s37, s37, 0x100
	s_addc_u32 s51, s51, 0
	s_add_u32 s12, s12, 0x100
	s_addc_u32 s13, s13, 0
	global_load_lds_dwordx4 v[180:181], off
	s_add_i32 m0, s58, 0x2000
	s_add_u32 s14, s14, 0x40080
	v_lshl_add_u64 v[180:181], v[218:219], 0, s[10:11]
	s_addc_u32 s15, s15, 0
	s_add_i32 s58, s71, s62
	global_load_lds_dwordx4 v[180:181], off
	s_mov_b32 m0, s58
	v_lshl_add_u64 v[180:181], s[14:15], 0, v[0:1]
	global_load_lds_dwordx4 v[180:181], off
	s_add_i32 m0, s58, 0x2000
	v_lshl_add_u64 v[180:181], s[14:15], 0, v[154:155]
	global_load_lds_dwordx4 v[180:181], off
	s_mov_b32 m0, s67
	v_lshl_add_u64 v[180:181], v[220:221], 0, s[10:11]
	global_load_lds_dwordx4 v[180:181], off
	s_mov_b32 m0, s68
	v_lshl_add_u64 v[180:181], v[222:223], 0, s[10:11]
	global_load_lds_dwordx4 v[180:181], off
	s_waitcnt vmcnt(8)
	s_waitcnt lgkmcnt(0)
	s_setprio 1
	s_barrier
	v_mfma_f32_16x16x32_bf16 v[62:65], v[114:117], v[172:175], v[62:65]
	v_mfma_f32_16x16x32_bf16 v[58:61], v[122:125], v[172:175], v[58:61]
	v_mfma_f32_16x16x32_bf16 v[46:49], v[114:117], v[186:189], v[46:49]
	v_mfma_f32_16x16x32_bf16 v[42:45], v[122:125], v[186:189], v[42:45]
	v_mfma_f32_16x16x32_bf16 v[30:33], v[114:117], v[202:205], v[30:33]
	v_mfma_f32_16x16x32_bf16 v[26:29], v[122:125], v[202:205], v[26:29]
	v_mfma_f32_16x16x32_bf16 v[14:17], v[114:117], v[210:213], v[14:17]
	v_mfma_f32_16x16x32_bf16 v[10:13], v[122:125], v[210:213], v[10:13]
	v_mfma_f32_16x16x32_bf16 v[62:65], v[118:121], v[176:179], v[62:65]
	v_mfma_f32_16x16x32_bf16 v[58:61], v[134:137], v[176:179], v[58:61]
	v_mfma_f32_16x16x32_bf16 v[46:49], v[118:121], v[190:193], v[46:49]
	v_mfma_f32_16x16x32_bf16 v[42:45], v[134:137], v[190:193], v[42:45]
	v_mfma_f32_16x16x32_bf16 v[30:33], v[118:121], v[206:209], v[30:33]
	v_mfma_f32_16x16x32_bf16 v[26:29], v[134:137], v[206:209], v[26:29]
	v_mfma_f32_16x16x32_bf16 v[14:17], v[118:121], v[214:217], v[14:17]
	v_mfma_f32_16x16x32_bf16 v[10:13], v[134:137], v[214:217], v[10:13]
	v_mfma_f32_16x16x32_bf16 v[54:57], v[146:149], v[172:175], v[54:57]
	v_mfma_f32_16x16x32_bf16 v[50:53], v[164:167], v[172:175], v[50:53]
	v_mfma_f32_16x16x32_bf16 v[38:41], v[146:149], v[186:189], v[38:41]
	v_mfma_f32_16x16x32_bf16 v[34:37], v[164:167], v[186:189], v[34:37]
	v_mfma_f32_16x16x32_bf16 v[22:25], v[146:149], v[202:205], v[22:25]
	v_mfma_f32_16x16x32_bf16 v[18:21], v[164:167], v[202:205], v[18:21]
	v_mfma_f32_16x16x32_bf16 v[6:9], v[146:149], v[210:213], v[6:9]
	v_mfma_f32_16x16x32_bf16 v[2:5], v[164:167], v[210:213], v[2:5]
	v_mfma_f32_16x16x32_bf16 v[54:57], v[150:153], v[176:179], v[54:57]
	v_mfma_f32_16x16x32_bf16 v[50:53], v[168:171], v[176:179], v[50:53]
	v_mfma_f32_16x16x32_bf16 v[38:41], v[150:153], v[190:193], v[38:41]
	v_mfma_f32_16x16x32_bf16 v[34:37], v[168:171], v[190:193], v[34:37]
	v_mfma_f32_16x16x32_bf16 v[22:25], v[150:153], v[206:209], v[22:25]
	v_mfma_f32_16x16x32_bf16 v[18:21], v[168:171], v[206:209], v[18:21]
	v_mfma_f32_16x16x32_bf16 v[6:9], v[150:153], v[214:217], v[6:9]
	v_mfma_f32_16x16x32_bf16 v[2:5], v[168:171], v[214:217], v[2:5]
	s_barrier
	s_setprio 0
	s_cmp_gt_u32 s53, 13
	s_cbranch_scc0 .LBB0_481
	s_and_b64 vcc, exec, s[48:49]
	s_cbranch_vccz .LBB0_484
	s_barrier

.LBB0_561:
	s_add_i32 s66, 0, 0x10000
	v_add_u32_e32 v140, s66, v145
	s_add_i32 s68, 0, 0x14000
	ds_read_b128 v[150:153], v140
	ds_read_b128 v[154:157], v140 offset:1024
	ds_read_b128 v[158:161], v140 offset:2048
	ds_read_b128 v[162:165], v140 offset:3072
	v_add_u32_e32 v140, s68, v145
	ds_read_b128 v[166:169], v140
	ds_read_b128 v[170:173], v140 offset:1024
	ds_read_b128 v[174:177], v140 offset:2048
	ds_read_b128 v[178:181], v140 offset:3072
	v_lshl_add_u64 v[142:143], s[12:13], 0, v[138:139]
	s_add_i32 m0, s59, 0xc000
	ds_read_b128 v[182:185], v149
	ds_read_b128 v[186:189], v149 offset:1024
	ds_read_b128 v[190:193], v149 offset:2048
	ds_read_b128 v[202:205], v149 offset:3072
	ds_read_b128 v[206:209], v149 offset:4096
	ds_read_b128 v[210:213], v149 offset:5120
	ds_read_b128 v[214:217], v149 offset:6144
	ds_read_b128 v[218:221], v149 offset:7168
	s_add_u32 s14, s12, 0xfffc0080
	s_addc_u32 s15, s13, -1
	s_cmp_eq_u32 s49, 12
	s_cselect_b32 s55, s28, s15
	s_cselect_b32 s54, s29, s14
	s_cselect_b32 s15, s33, s47
	s_cselect_b32 s14, s36, s37
	global_load_lds_dwordx4 v[142:143], off
	s_add_i32 m0, s59, 0xe000
	v_lshl_add_u64 v[142:143], s[12:13], 0, v[136:137]
	global_load_lds_dwordx4 v[142:143], off
	s_waitcnt vmcnt(8)
	s_waitcnt lgkmcnt(0)
	s_setprio 1
	s_barrier
	v_mfma_f32_16x16x32_bf16 v[126:129], v[150:153], v[182:185], v[126:129]
	v_mfma_f32_16x16x32_bf16 v[122:125], v[158:161], v[182:185], v[122:125]
	v_mfma_f32_16x16x32_bf16 v[110:113], v[150:153], v[190:193], v[110:113]
	v_mfma_f32_16x16x32_bf16 v[106:109], v[158:161], v[190:193], v[106:109]
	v_mfma_f32_16x16x32_bf16 v[94:97], v[150:153], v[206:209], v[94:97]
	v_mfma_f32_16x16x32_bf16 v[90:93], v[158:161], v[206:209], v[90:93]
	v_mfma_f32_16x16x32_bf16 v[78:81], v[150:153], v[214:217], v[78:81]
	v_mfma_f32_16x16x32_bf16 v[74:77], v[158:161], v[214:217], v[74:77]
	v_mfma_f32_16x16x32_bf16 v[126:129], v[154:157], v[186:189], v[126:129]
	v_mfma_f32_16x16x32_bf16 v[122:125], v[162:165], v[186:189], v[122:125]
	v_mfma_f32_16x16x32_bf16 v[110:113], v[154:157], v[202:205], v[110:113]
	v_mfma_f32_16x16x32_bf16 v[106:109], v[162:165], v[202:205], v[106:109]
	v_mfma_f32_16x16x32_bf16 v[94:97], v[154:157], v[210:213], v[94:97]
	v_mfma_f32_16x16x32_bf16 v[90:93], v[162:165], v[210:213], v[90:93]
	v_mfma_f32_16x16x32_bf16 v[78:81], v[154:157], v[218:221], v[78:81]
	v_mfma_f32_16x16x32_bf16 v[74:77], v[162:165], v[218:221], v[74:77]
	v_mfma_f32_16x16x32_bf16 v[118:121], v[166:169], v[182:185], v[118:121]
	v_mfma_f32_16x16x32_bf16 v[114:117], v[174:177], v[182:185], v[114:117]
	v_mfma_f32_16x16x32_bf16 v[102:105], v[166:169], v[190:193], v[102:105]
	v_mfma_f32_16x16x32_bf16 v[98:101], v[174:177], v[190:193], v[98:101]
	v_mfma_f32_16x16x32_bf16 v[86:89], v[166:169], v[206:209], v[86:89]
	v_mfma_f32_16x16x32_bf16 v[82:85], v[174:177], v[206:209], v[82:85]
	v_mfma_f32_16x16x32_bf16 v[70:73], v[166:169], v[214:217], v[70:73]
	v_mfma_f32_16x16x32_bf16 v[66:69], v[174:177], v[214:217], v[66:69]
	v_mfma_f32_16x16x32_bf16 v[118:121], v[170:173], v[186:189], v[118:121]
	v_mfma_f32_16x16x32_bf16 v[114:117], v[178:181], v[186:189], v[114:117]
	v_mfma_f32_16x16x32_bf16 v[102:105], v[170:173], v[202:205], v[102:105]
	v_mfma_f32_16x16x32_bf16 v[98:101], v[178:181], v[202:205], v[98:101]
	v_mfma_f32_16x16x32_bf16 v[86:89], v[170:173], v[210:213], v[86:89]
	v_mfma_f32_16x16x32_bf16 v[82:85], v[178:181], v[210:213], v[82:85]
	v_mfma_f32_16x16x32_bf16 v[70:73], v[170:173], v[218:221], v[70:73]
	v_mfma_f32_16x16x32_bf16 v[66:69], v[178:181], v[218:221], v[66:69]
	s_barrier
	s_setprio 0
	s_add_i32 s66, s66, s58
	v_lshl_add_u64 v[142:143], s[14:15], 0, v[0:1]
	s_mov_b32 m0, s66
	ds_read_b128 v[182:185], v149 offset:16384
	ds_read_b128 v[186:189], v149 offset:17408
	ds_read_b128 v[190:193], v149 offset:18432
	ds_read_b128 v[202:205], v149 offset:19456
	ds_read_b128 v[206:209], v149 offset:20480
	ds_read_b128 v[210:213], v149 offset:21504
	ds_read_b128 v[214:217], v149 offset:22528
	ds_read_b128 v[218:221], v149 offset:23552
	global_load_lds_dwordx4 v[142:143], off
	s_add_i32 m0, s66, 0x2000
	s_add_u32 s66, s14, 0x40000
	v_lshl_add_u64 v[222:223], s[14:15], 0, v[130:131]
	s_addc_u32 s67, s15, 0
	s_add_i32 s68, s68, s58
	global_load_lds_dwordx4 v[222:223], off
	v_lshl_add_u64 v[232:233], s[66:67], 0, v[0:1]
	s_mov_b32 m0, s68
	v_lshl_add_u64 v[234:235], s[54:55], 0, v[132:133]
	global_load_lds_dwordx4 v[232:233], off
	s_add_i32 m0, s68, 0x2000
	v_lshl_add_u64 v[232:233], s[66:67], 0, v[130:131]
	global_load_lds_dwordx4 v[232:233], off
	s_mov_b32 m0, s59
	v_lshl_add_u64 v[232:233], s[54:55], 0, v[134:135]
	global_load_lds_dwordx4 v[232:233], off
	s_mov_b32 m0, s60
	s_nop 0
	global_load_lds_dwordx4 v[234:235], off
	s_waitcnt vmcnt(8)
	s_waitcnt lgkmcnt(0)
	s_setprio 1
	s_barrier
	v_mfma_f32_16x16x32_bf16 v[62:65], v[150:153], v[182:185], v[62:65]
	v_mfma_f32_16x16x32_bf16 v[58:61], v[158:161], v[182:185], v[58:61]
	v_mfma_f32_16x16x32_bf16 v[46:49], v[150:153], v[190:193], v[46:49]
	v_mfma_f32_16x16x32_bf16 v[42:45], v[158:161], v[190:193], v[42:45]
	v_mfma_f32_16x16x32_bf16 v[30:33], v[150:153], v[206:209], v[30:33]
	v_mfma_f32_16x16x32_bf16 v[26:29], v[158:161], v[206:209], v[26:29]
	v_mfma_f32_16x16x32_bf16 v[14:17], v[150:153], v[214:217], v[14:17]
	v_mfma_f32_16x16x32_bf16 v[10:13], v[158:161], v[214:217], v[10:13]
	v_mfma_f32_16x16x32_bf16 v[62:65], v[154:157], v[186:189], v[62:65]
	v_mfma_f32_16x16x32_bf16 v[58:61], v[162:165], v[186:189], v[58:61]
	v_mfma_f32_16x16x32_bf16 v[46:49], v[154:157], v[202:205], v[46:49]
	v_mfma_f32_16x16x32_bf16 v[42:45], v[162:165], v[202:205], v[42:45]
	v_mfma_f32_16x16x32_bf16 v[30:33], v[154:157], v[210:213], v[30:33]
	v_mfma_f32_16x16x32_bf16 v[26:29], v[162:165], v[210:213], v[26:29]
	v_mfma_f32_16x16x32_bf16 v[14:17], v[154:157], v[218:221], v[14:17]
	v_mfma_f32_16x16x32_bf16 v[10:13], v[162:165], v[218:221], v[10:13]
	v_mfma_f32_16x16x32_bf16 v[54:57], v[166:169], v[182:185], v[54:57]
	v_mfma_f32_16x16x32_bf16 v[50:53], v[174:177], v[182:185], v[50:53]
	v_mfma_f32_16x16x32_bf16 v[38:41], v[166:169], v[190:193], v[38:41]
	v_mfma_f32_16x16x32_bf16 v[34:37], v[174:177], v[190:193], v[34:37]
	v_mfma_f32_16x16x32_bf16 v[22:25], v[166:169], v[206:209], v[22:25]
	v_mfma_f32_16x16x32_bf16 v[18:21], v[174:177], v[206:209], v[18:21]
	v_mfma_f32_16x16x32_bf16 v[6:9], v[166:169], v[214:217], v[6:9]
	v_mfma_f32_16x16x32_bf16 v[2:5], v[174:177], v[214:217], v[2:5]
	v_mfma_f32_16x16x32_bf16 v[54:57], v[170:173], v[186:189], v[54:57]
	v_mfma_f32_16x16x32_bf16 v[50:53], v[178:181], v[186:189], v[50:53]
	v_mfma_f32_16x16x32_bf16 v[38:41], v[170:173], v[202:205], v[38:41]
	v_mfma_f32_16x16x32_bf16 v[34:37], v[178:181], v[202:205], v[34:37]
	v_mfma_f32_16x16x32_bf16 v[22:25], v[170:173], v[210:213], v[22:25]
	v_mfma_f32_16x16x32_bf16 v[18:21], v[178:181], v[210:213], v[18:21]
	v_mfma_f32_16x16x32_bf16 v[6:9], v[170:173], v[218:221], v[6:9]
	v_mfma_f32_16x16x32_bf16 v[2:5], v[178:181], v[218:221], v[2:5]
	s_barrier
	s_setprio 0
	s_add_i32 s66, 0, 0x18000
	v_add_u32_e32 v140, s66, v145
	s_add_i32 s67, 0, 0x1c000
	ds_read_b128 v[150:153], v140
	ds_read_b128 v[154:157], v140 offset:1024
	ds_read_b128 v[158:161], v140 offset:2048
	ds_read_b128 v[162:165], v140 offset:3072
	v_add_u32_e32 v140, s67, v145
	ds_read_b128 v[166:169], v140
	ds_read_b128 v[170:173], v140 offset:1024
	ds_read_b128 v[174:177], v140 offset:2048
	ds_read_b128 v[178:181], v140 offset:3072
	s_add_u32 s54, s54, 0x40000
	s_addc_u32 s55, s55, 0
	s_mov_b32 m0, s61
	v_lshl_add_u64 v[236:237], s[54:55], 0, v[134:135]
	ds_read_b128 v[182:185], v149 offset:32768
	ds_read_b128 v[186:189], v149 offset:33792
	ds_read_b128 v[190:193], v149 offset:34816
	ds_read_b128 v[202:205], v149 offset:35840
	ds_read_b128 v[206:209], v149 offset:36864
	ds_read_b128 v[210:213], v149 offset:37888
	ds_read_b128 v[214:217], v149 offset:38912
	ds_read_b128 v[218:221], v149 offset:39936
	global_load_lds_dwordx4 v[236:237], off
	s_mov_b32 m0, s62
	v_lshl_add_u64 v[236:237], s[54:55], 0, v[132:133]
	global_load_lds_dwordx4 v[236:237], off
	s_waitcnt vmcnt(8)
	s_waitcnt lgkmcnt(0)
	s_setprio 1
	s_barrier
	v_mfma_f32_16x16x32_bf16 v[126:129], v[150:153], v[182:185], v[126:129]
	v_mfma_f32_16x16x32_bf16 v[122:125], v[158:161], v[182:185], v[122:125]
	v_mfma_f32_16x16x32_bf16 v[110:113], v[150:153], v[190:193], v[110:113]
	v_mfma_f32_16x16x32_bf16 v[106:109], v[158:161], v[190:193], v[106:109]
	v_mfma_f32_16x16x32_bf16 v[94:97], v[150:153], v[206:209], v[94:97]
	v_mfma_f32_16x16x32_bf16 v[90:93], v[158:161], v[206:209], v[90:93]
	v_mfma_f32_16x16x32_bf16 v[78:81], v[150:153], v[214:217], v[78:81]
	v_mfma_f32_16x16x32_bf16 v[74:77], v[158:161], v[214:217], v[74:77]
	v_mfma_f32_16x16x32_bf16 v[126:129], v[154:157], v[186:189], v[126:129]
	v_mfma_f32_16x16x32_bf16 v[122:125], v[162:165], v[186:189], v[122:125]
	v_mfma_f32_16x16x32_bf16 v[110:113], v[154:157], v[202:205], v[110:113]
	v_mfma_f32_16x16x32_bf16 v[106:109], v[162:165], v[202:205], v[106:109]
	v_mfma_f32_16x16x32_bf16 v[94:97], v[154:157], v[210:213], v[94:97]
	v_mfma_f32_16x16x32_bf16 v[90:93], v[162:165], v[210:213], v[90:93]
	v_mfma_f32_16x16x32_bf16 v[78:81], v[154:157], v[218:221], v[78:81]
	v_mfma_f32_16x16x32_bf16 v[74:77], v[162:165], v[218:221], v[74:77]
	v_mfma_f32_16x16x32_bf16 v[118:121], v[166:169], v[182:185], v[118:121]
	v_mfma_f32_16x16x32_bf16 v[114:117], v[174:177], v[182:185], v[114:117]
	v_mfma_f32_16x16x32_bf16 v[102:105], v[166:169], v[190:193], v[102:105]
	v_mfma_f32_16x16x32_bf16 v[98:101], v[174:177], v[190:193], v[98:101]
	v_mfma_f32_16x16x32_bf16 v[86:89], v[166:169], v[206:209], v[86:89]
	v_mfma_f32_16x16x32_bf16 v[82:85], v[174:177], v[206:209], v[82:85]
	v_mfma_f32_16x16x32_bf16 v[70:73], v[166:169], v[214:217], v[70:73]
	v_mfma_f32_16x16x32_bf16 v[66:69], v[174:177], v[214:217], v[66:69]
	v_mfma_f32_16x16x32_bf16 v[118:121], v[170:173], v[186:189], v[118:121]
	v_mfma_f32_16x16x32_bf16 v[114:117], v[178:181], v[186:189], v[114:117]
	v_mfma_f32_16x16x32_bf16 v[102:105], v[170:173], v[202:205], v[102:105]
	v_mfma_f32_16x16x32_bf16 v[98:101], v[178:181], v[202:205], v[98:101]
	v_mfma_f32_16x16x32_bf16 v[86:89], v[170:173], v[210:213], v[86:89]
	v_mfma_f32_16x16x32_bf16 v[82:85], v[178:181], v[210:213], v[82:85]
	v_mfma_f32_16x16x32_bf16 v[70:73], v[170:173], v[218:221], v[70:73]
	v_mfma_f32_16x16x32_bf16 v[66:69], v[178:181], v[218:221], v[66:69]
	s_barrier
	s_setprio 0
	s_add_i32 s54, s66, s58
	v_lshl_add_u64 v[142:143], v[142:143], 0, s[10:11]
	s_mov_b32 m0, s54
	ds_read_b128 v[182:185], v149 offset:49152
	ds_read_b128 v[186:189], v149 offset:50176
	ds_read_b128 v[190:193], v149 offset:51200
	ds_read_b128 v[202:205], v149 offset:52224
	ds_read_b128 v[206:209], v149 offset:53248
	ds_read_b128 v[210:213], v149 offset:54272
	ds_read_b128 v[214:217], v149 offset:55296
	ds_read_b128 v[218:221], v149 offset:56320
	s_add_i32 s49, s49, 2
	s_add_u32 s37, s37, 0x100
	s_addc_u32 s47, s47, 0
	s_add_u32 s12, s12, 0x100
	s_addc_u32 s13, s13, 0
	global_load_lds_dwordx4 v[142:143], off
	s_add_i32 m0, s54, 0x2000
	s_add_u32 s14, s14, 0x40080
	v_lshl_add_u64 v[142:143], v[222:223], 0, s[10:11]
	s_addc_u32 s15, s15, 0
	s_add_i32 s54, s67, s58
	global_load_lds_dwordx4 v[142:143], off
	s_mov_b32 m0, s54
	v_lshl_add_u64 v[142:143], s[14:15], 0, v[0:1]
	global_load_lds_dwordx4 v[142:143], off
	s_add_i32 m0, s54, 0x2000
	v_lshl_add_u64 v[142:143], s[14:15], 0, v[130:131]
	global_load_lds_dwordx4 v[142:143], off
	s_mov_b32 m0, s63
	v_lshl_add_u64 v[142:143], v[232:233], 0, s[10:11]
	global_load_lds_dwordx4 v[142:143], off
	s_mov_b32 m0, s64
	v_lshl_add_u64 v[142:143], v[234:235], 0, s[10:11]
	global_load_lds_dwordx4 v[142:143], off
	s_waitcnt vmcnt(8)
	s_waitcnt lgkmcnt(0)
	s_setprio 1
	s_barrier
	v_mfma_f32_16x16x32_bf16 v[62:65], v[150:153], v[182:185], v[62:65]
	v_mfma_f32_16x16x32_bf16 v[58:61], v[158:161], v[182:185], v[58:61]
	v_mfma_f32_16x16x32_bf16 v[46:49], v[150:153], v[190:193], v[46:49]
	v_mfma_f32_16x16x32_bf16 v[42:45], v[158:161], v[190:193], v[42:45]
	v_mfma_f32_16x16x32_bf16 v[30:33], v[150:153], v[206:209], v[30:33]
	v_mfma_f32_16x16x32_bf16 v[26:29], v[158:161], v[206:209], v[26:29]
	v_mfma_f32_16x16x32_bf16 v[14:17], v[150:153], v[214:217], v[14:17]
	v_mfma_f32_16x16x32_bf16 v[10:13], v[158:161], v[214:217], v[10:13]
	v_mfma_f32_16x16x32_bf16 v[62:65], v[154:157], v[186:189], v[62:65]
	v_mfma_f32_16x16x32_bf16 v[58:61], v[162:165], v[186:189], v[58:61]
	v_mfma_f32_16x16x32_bf16 v[46:49], v[154:157], v[202:205], v[46:49]
	v_mfma_f32_16x16x32_bf16 v[42:45], v[162:165], v[202:205], v[42:45]
	v_mfma_f32_16x16x32_bf16 v[30:33], v[154:157], v[210:213], v[30:33]
	v_mfma_f32_16x16x32_bf16 v[26:29], v[162:165], v[210:213], v[26:29]
	v_mfma_f32_16x16x32_bf16 v[14:17], v[154:157], v[218:221], v[14:17]
	v_mfma_f32_16x16x32_bf16 v[10:13], v[162:165], v[218:221], v[10:13]
	v_mfma_f32_16x16x32_bf16 v[54:57], v[166:169], v[182:185], v[54:57]
	v_mfma_f32_16x16x32_bf16 v[50:53], v[174:177], v[182:185], v[50:53]
	v_mfma_f32_16x16x32_bf16 v[38:41], v[166:169], v[190:193], v[38:41]
	v_mfma_f32_16x16x32_bf16 v[34:37], v[174:177], v[190:193], v[34:37]
	v_mfma_f32_16x16x32_bf16 v[22:25], v[166:169], v[206:209], v[22:25]
	v_mfma_f32_16x16x32_bf16 v[18:21], v[174:177], v[206:209], v[18:21]
	v_mfma_f32_16x16x32_bf16 v[6:9], v[166:169], v[214:217], v[6:9]
	v_mfma_f32_16x16x32_bf16 v[2:5], v[174:177], v[214:217], v[2:5]
	v_mfma_f32_16x16x32_bf16 v[54:57], v[170:173], v[186:189], v[54:57]
	v_mfma_f32_16x16x32_bf16 v[50:53], v[178:181], v[186:189], v[50:53]
	v_mfma_f32_16x16x32_bf16 v[38:41], v[170:173], v[202:205], v[38:41]
	v_mfma_f32_16x16x32_bf16 v[34:37], v[178:181], v[202:205], v[34:37]
	v_mfma_f32_16x16x32_bf16 v[22:25], v[170:173], v[210:213], v[22:25]
	v_mfma_f32_16x16x32_bf16 v[18:21], v[178:181], v[210:213], v[18:21]
	v_mfma_f32_16x16x32_bf16 v[6:9], v[170:173], v[218:221], v[6:9]
	v_mfma_f32_16x16x32_bf16 v[2:5], v[178:181], v[218:221], v[2:5]
	s_barrier
	s_setprio 0
	s_cmp_gt_u32 s49, 13
	s_cbranch_scc0 .LBB0_561
	s_and_b64 vcc, exec, s[44:45]
	s_cbranch_vccz .LBB0_564
	s_barrier

.LBB0_626:
	s_add_i32 s70, 0, 0x10000
	s_add_i32 s72, 0, 0x14000
	v_add_u32_e32 v134, s70, v183
	v_add_u32_e32 v168, s72, v183
	ds_read_b128 v[114:117], v134
	ds_read_b128 v[118:121], v134 offset:1024
	ds_read_b128 v[122:125], v134 offset:2048
	ds_read_b128 v[134:137], v134 offset:3072
	ds_read_b128 v[146:149], v168
	ds_read_b128 v[150:153], v168 offset:1024
	ds_read_b128 v[164:167], v168 offset:2048
	ds_read_b128 v[168:171], v168 offset:3072
	v_lshl_add_u64 v[180:181], s[12:13], 0, v[162:163]
	s_add_i32 m0, s63, 0xc000
	ds_read_b128 v[172:175], v185
	ds_read_b128 v[176:179], v185 offset:1024
	ds_read_b128 v[186:189], v185 offset:2048
	ds_read_b128 v[190:193], v185 offset:3072
	ds_read_b128 v[202:205], v185 offset:4096
	ds_read_b128 v[206:209], v185 offset:5120
	ds_read_b128 v[210:213], v185 offset:6144
	ds_read_b128 v[214:217], v185 offset:7168
	s_add_u32 s14, s12, 0xfff00080
	s_addc_u32 s15, s13, -1
	s_cmp_eq_u32 s53, 60
	s_cselect_b32 s59, s28, s15
	s_cselect_b32 s58, s29, s14
	s_cselect_b32 s15, s33, s51
	s_cselect_b32 s14, s36, s37
	global_load_lds_dwordx4 v[180:181], off
	s_add_i32 m0, s63, 0xe000
	v_lshl_add_u64 v[180:181], s[12:13], 0, v[160:161]
	global_load_lds_dwordx4 v[180:181], off
	s_waitcnt vmcnt(8)
	s_waitcnt lgkmcnt(0)
	s_setprio 1
	s_barrier
	v_mfma_f32_16x16x32_bf16 v[142:145], v[114:117], v[172:175], v[142:145]
	v_mfma_f32_16x16x32_bf16 v[138:141], v[122:125], v[172:175], v[138:141]
	v_mfma_f32_16x16x32_bf16 v[110:113], v[114:117], v[186:189], v[110:113]
	v_mfma_f32_16x16x32_bf16 v[106:109], v[122:125], v[186:189], v[106:109]
	v_mfma_f32_16x16x32_bf16 v[94:97], v[114:117], v[202:205], v[94:97]
	v_mfma_f32_16x16x32_bf16 v[90:93], v[122:125], v[202:205], v[90:93]
	v_mfma_f32_16x16x32_bf16 v[78:81], v[114:117], v[210:213], v[78:81]
	v_mfma_f32_16x16x32_bf16 v[74:77], v[122:125], v[210:213], v[74:77]
	v_mfma_f32_16x16x32_bf16 v[142:145], v[118:121], v[176:179], v[142:145]
	v_mfma_f32_16x16x32_bf16 v[138:141], v[134:137], v[176:179], v[138:141]
	v_mfma_f32_16x16x32_bf16 v[110:113], v[118:121], v[190:193], v[110:113]
	v_mfma_f32_16x16x32_bf16 v[106:109], v[134:137], v[190:193], v[106:109]
	v_mfma_f32_16x16x32_bf16 v[94:97], v[118:121], v[206:209], v[94:97]
	v_mfma_f32_16x16x32_bf16 v[90:93], v[134:137], v[206:209], v[90:93]
	v_mfma_f32_16x16x32_bf16 v[78:81], v[118:121], v[214:217], v[78:81]
	v_mfma_f32_16x16x32_bf16 v[74:77], v[134:137], v[214:217], v[74:77]
	v_mfma_f32_16x16x32_bf16 v[130:133], v[146:149], v[172:175], v[130:133]
	v_mfma_f32_16x16x32_bf16 v[126:129], v[164:167], v[172:175], v[126:129]
	v_mfma_f32_16x16x32_bf16 v[102:105], v[146:149], v[186:189], v[102:105]
	v_mfma_f32_16x16x32_bf16 v[98:101], v[164:167], v[186:189], v[98:101]
	v_mfma_f32_16x16x32_bf16 v[86:89], v[146:149], v[202:205], v[86:89]
	v_mfma_f32_16x16x32_bf16 v[82:85], v[164:167], v[202:205], v[82:85]
	v_mfma_f32_16x16x32_bf16 v[70:73], v[146:149], v[210:213], v[70:73]
	v_mfma_f32_16x16x32_bf16 v[66:69], v[164:167], v[210:213], v[66:69]
	v_mfma_f32_16x16x32_bf16 v[130:133], v[150:153], v[176:179], v[130:133]
	v_mfma_f32_16x16x32_bf16 v[126:129], v[168:171], v[176:179], v[126:129]
	v_mfma_f32_16x16x32_bf16 v[102:105], v[150:153], v[190:193], v[102:105]
	v_mfma_f32_16x16x32_bf16 v[98:101], v[168:171], v[190:193], v[98:101]
	v_mfma_f32_16x16x32_bf16 v[86:89], v[150:153], v[206:209], v[86:89]
	v_mfma_f32_16x16x32_bf16 v[82:85], v[168:171], v[206:209], v[82:85]
	v_mfma_f32_16x16x32_bf16 v[70:73], v[150:153], v[214:217], v[70:73]
	v_mfma_f32_16x16x32_bf16 v[66:69], v[168:171], v[214:217], v[66:69]
	s_barrier
	s_setprio 0
	s_add_i32 s70, s70, s62
	v_lshl_add_u64 v[180:181], s[14:15], 0, v[0:1]
	s_mov_b32 m0, s70
	ds_read_b128 v[172:175], v185 offset:16384
	ds_read_b128 v[176:179], v185 offset:17408
	ds_read_b128 v[186:189], v185 offset:18432
	ds_read_b128 v[190:193], v185 offset:19456
	ds_read_b128 v[202:205], v185 offset:20480
	ds_read_b128 v[206:209], v185 offset:21504
	ds_read_b128 v[210:213], v185 offset:22528
	ds_read_b128 v[214:217], v185 offset:23552
	global_load_lds_dwordx4 v[180:181], off
	s_add_i32 m0, s70, 0x2000
	s_add_u32 s70, s14, 0x100000
	v_lshl_add_u64 v[218:219], s[14:15], 0, v[154:155]
	s_addc_u32 s71, s15, 0
	s_add_i32 s72, s72, s62
	global_load_lds_dwordx4 v[218:219], off
	v_lshl_add_u64 v[220:221], s[70:71], 0, v[0:1]
	s_mov_b32 m0, s72
	v_lshl_add_u64 v[222:223], s[58:59], 0, v[156:157]
	global_load_lds_dwordx4 v[220:221], off
	s_add_i32 m0, s72, 0x2000
	v_lshl_add_u64 v[220:221], s[70:71], 0, v[154:155]
	global_load_lds_dwordx4 v[220:221], off
	s_mov_b32 m0, s63
	v_lshl_add_u64 v[220:221], s[58:59], 0, v[158:159]
	global_load_lds_dwordx4 v[220:221], off
	s_mov_b32 m0, s64
	s_nop 0
	global_load_lds_dwordx4 v[222:223], off
	s_waitcnt vmcnt(8)
	s_waitcnt lgkmcnt(0)
	s_setprio 1
	s_barrier
	v_mfma_f32_16x16x32_bf16 v[62:65], v[114:117], v[172:175], v[62:65]
	v_mfma_f32_16x16x32_bf16 v[58:61], v[122:125], v[172:175], v[58:61]
	v_mfma_f32_16x16x32_bf16 v[46:49], v[114:117], v[186:189], v[46:49]
	v_mfma_f32_16x16x32_bf16 v[42:45], v[122:125], v[186:189], v[42:45]
	v_mfma_f32_16x16x32_bf16 v[30:33], v[114:117], v[202:205], v[30:33]
	v_mfma_f32_16x16x32_bf16 v[26:29], v[122:125], v[202:205], v[26:29]
	v_mfma_f32_16x16x32_bf16 v[14:17], v[114:117], v[210:213], v[14:17]
	v_mfma_f32_16x16x32_bf16 v[10:13], v[122:125], v[210:213], v[10:13]
	v_mfma_f32_16x16x32_bf16 v[62:65], v[118:121], v[176:179], v[62:65]
	v_mfma_f32_16x16x32_bf16 v[58:61], v[134:137], v[176:179], v[58:61]
	v_mfma_f32_16x16x32_bf16 v[46:49], v[118:121], v[190:193], v[46:49]
	v_mfma_f32_16x16x32_bf16 v[42:45], v[134:137], v[190:193], v[42:45]
	v_mfma_f32_16x16x32_bf16 v[30:33], v[118:121], v[206:209], v[30:33]
	v_mfma_f32_16x16x32_bf16 v[26:29], v[134:137], v[206:209], v[26:29]
	v_mfma_f32_16x16x32_bf16 v[14:17], v[118:121], v[214:217], v[14:17]
	v_mfma_f32_16x16x32_bf16 v[10:13], v[134:137], v[214:217], v[10:13]
	v_mfma_f32_16x16x32_bf16 v[54:57], v[146:149], v[172:175], v[54:57]
	v_mfma_f32_16x16x32_bf16 v[50:53], v[164:167], v[172:175], v[50:53]
	v_mfma_f32_16x16x32_bf16 v[38:41], v[146:149], v[186:189], v[38:41]
	v_mfma_f32_16x16x32_bf16 v[34:37], v[164:167], v[186:189], v[34:37]
	v_mfma_f32_16x16x32_bf16 v[22:25], v[146:149], v[202:205], v[22:25]
	v_mfma_f32_16x16x32_bf16 v[18:21], v[164:167], v[202:205], v[18:21]
	v_mfma_f32_16x16x32_bf16 v[6:9], v[146:149], v[210:213], v[6:9]
	v_mfma_f32_16x16x32_bf16 v[2:5], v[164:167], v[210:213], v[2:5]
	v_mfma_f32_16x16x32_bf16 v[54:57], v[150:153], v[176:179], v[54:57]
	v_mfma_f32_16x16x32_bf16 v[50:53], v[168:171], v[176:179], v[50:53]
	v_mfma_f32_16x16x32_bf16 v[38:41], v[150:153], v[190:193], v[38:41]
	v_mfma_f32_16x16x32_bf16 v[34:37], v[168:171], v[190:193], v[34:37]
	v_mfma_f32_16x16x32_bf16 v[22:25], v[150:153], v[206:209], v[22:25]
	v_mfma_f32_16x16x32_bf16 v[18:21], v[168:171], v[206:209], v[18:21]
	v_mfma_f32_16x16x32_bf16 v[6:9], v[150:153], v[214:217], v[6:9]
	v_mfma_f32_16x16x32_bf16 v[2:5], v[168:171], v[214:217], v[2:5]
	s_barrier
	s_setprio 0
	s_add_i32 s70, 0, 0x18000
	s_add_i32 s71, 0, 0x1c000
	v_add_u32_e32 v134, s70, v183
	v_add_u32_e32 v168, s71, v183
	ds_read_b128 v[114:117], v134
	ds_read_b128 v[118:121], v134 offset:1024
	ds_read_b128 v[122:125], v134 offset:2048
	ds_read_b128 v[134:137], v134 offset:3072
	ds_read_b128 v[146:149], v168
	ds_read_b128 v[150:153], v168 offset:1024
	ds_read_b128 v[164:167], v168 offset:2048
	ds_read_b128 v[168:171], v168 offset:3072
	s_add_u32 s58, s58, 0x100000
	s_addc_u32 s59, s59, 0
	s_mov_b32 m0, s65
	v_lshl_add_u64 v[232:233], s[58:59], 0, v[158:159]
	ds_read_b128 v[172:175], v185 offset:32768
	ds_read_b128 v[176:179], v185 offset:33792
	ds_read_b128 v[186:189], v185 offset:34816
	ds_read_b128 v[190:193], v185 offset:35840
	ds_read_b128 v[202:205], v185 offset:36864
	ds_read_b128 v[206:209], v185 offset:37888
	ds_read_b128 v[210:213], v185 offset:38912
	ds_read_b128 v[214:217], v185 offset:39936
	global_load_lds_dwordx4 v[232:233], off
	s_mov_b32 m0, s66
	v_lshl_add_u64 v[232:233], s[58:59], 0, v[156:157]
	global_load_lds_dwordx4 v[232:233], off
	s_waitcnt vmcnt(8)
	s_waitcnt lgkmcnt(0)
	s_setprio 1
	s_barrier
	v_mfma_f32_16x16x32_bf16 v[142:145], v[114:117], v[172:175], v[142:145]
	v_mfma_f32_16x16x32_bf16 v[138:141], v[122:125], v[172:175], v[138:141]
	v_mfma_f32_16x16x32_bf16 v[110:113], v[114:117], v[186:189], v[110:113]
	v_mfma_f32_16x16x32_bf16 v[106:109], v[122:125], v[186:189], v[106:109]
	v_mfma_f32_16x16x32_bf16 v[94:97], v[114:117], v[202:205], v[94:97]
	v_mfma_f32_16x16x32_bf16 v[90:93], v[122:125], v[202:205], v[90:93]
	v_mfma_f32_16x16x32_bf16 v[78:81], v[114:117], v[210:213], v[78:81]
	v_mfma_f32_16x16x32_bf16 v[74:77], v[122:125], v[210:213], v[74:77]
	v_mfma_f32_16x16x32_bf16 v[142:145], v[118:121], v[176:179], v[142:145]
	v_mfma_f32_16x16x32_bf16 v[138:141], v[134:137], v[176:179], v[138:141]
	v_mfma_f32_16x16x32_bf16 v[110:113], v[118:121], v[190:193], v[110:113]
	v_mfma_f32_16x16x32_bf16 v[106:109], v[134:137], v[190:193], v[106:109]
	v_mfma_f32_16x16x32_bf16 v[94:97], v[118:121], v[206:209], v[94:97]
	v_mfma_f32_16x16x32_bf16 v[90:93], v[134:137], v[206:209], v[90:93]
	v_mfma_f32_16x16x32_bf16 v[78:81], v[118:121], v[214:217], v[78:81]
	v_mfma_f32_16x16x32_bf16 v[74:77], v[134:137], v[214:217], v[74:77]
	v_mfma_f32_16x16x32_bf16 v[130:133], v[146:149], v[172:175], v[130:133]
	v_mfma_f32_16x16x32_bf16 v[126:129], v[164:167], v[172:175], v[126:129]
	v_mfma_f32_16x16x32_bf16 v[102:105], v[146:149], v[186:189], v[102:105]
	v_mfma_f32_16x16x32_bf16 v[98:101], v[164:167], v[186:189], v[98:101]
	v_mfma_f32_16x16x32_bf16 v[86:89], v[146:149], v[202:205], v[86:89]
	v_mfma_f32_16x16x32_bf16 v[82:85], v[164:167], v[202:205], v[82:85]
	v_mfma_f32_16x16x32_bf16 v[70:73], v[146:149], v[210:213], v[70:73]
	v_mfma_f32_16x16x32_bf16 v[66:69], v[164:167], v[210:213], v[66:69]
	v_mfma_f32_16x16x32_bf16 v[130:133], v[150:153], v[176:179], v[130:133]
	v_mfma_f32_16x16x32_bf16 v[126:129], v[168:171], v[176:179], v[126:129]
	v_mfma_f32_16x16x32_bf16 v[102:105], v[150:153], v[190:193], v[102:105]
	v_mfma_f32_16x16x32_bf16 v[98:101], v[168:171], v[190:193], v[98:101]
	v_mfma_f32_16x16x32_bf16 v[86:89], v[150:153], v[206:209], v[86:89]
	v_mfma_f32_16x16x32_bf16 v[82:85], v[168:171], v[206:209], v[82:85]
	v_mfma_f32_16x16x32_bf16 v[70:73], v[150:153], v[214:217], v[70:73]
	v_mfma_f32_16x16x32_bf16 v[66:69], v[168:171], v[214:217], v[66:69]
	s_barrier
	s_setprio 0
	s_add_i32 s58, s70, s62
	v_lshl_add_u64 v[180:181], v[180:181], 0, s[10:11]
	s_mov_b32 m0, s58
	ds_read_b128 v[172:175], v185 offset:49152
	ds_read_b128 v[176:179], v185 offset:50176
	ds_read_b128 v[186:189], v185 offset:51200
	ds_read_b128 v[190:193], v185 offset:52224
	ds_read_b128 v[202:205], v185 offset:53248
	ds_read_b128 v[206:209], v185 offset:54272
	ds_read_b128 v[210:213], v185 offset:55296
	ds_read_b128 v[214:217], v185 offset:56320
	s_add_i32 s53, s53, 2
	s_add_u32 s37, s37, 0x100
	s_addc_u32 s51, s51, 0
	s_add_u32 s12, s12, 0x100
	s_addc_u32 s13, s13, 0
	global_load_lds_dwordx4 v[180:181], off
	s_add_i32 m0, s58, 0x2000
	s_add_u32 s14, s14, 0x100080
	v_lshl_add_u64 v[180:181], v[218:219], 0, s[10:11]
	s_addc_u32 s15, s15, 0
	s_add_i32 s58, s71, s62
	global_load_lds_dwordx4 v[180:181], off
	s_mov_b32 m0, s58
	v_lshl_add_u64 v[180:181], s[14:15], 0, v[0:1]
	global_load_lds_dwordx4 v[180:181], off
	s_add_i32 m0, s58, 0x2000
	v_lshl_add_u64 v[180:181], s[14:15], 0, v[154:155]
	global_load_lds_dwordx4 v[180:181], off
	s_mov_b32 m0, s67
	v_lshl_add_u64 v[180:181], v[220:221], 0, s[10:11]
	global_load_lds_dwordx4 v[180:181], off
	s_mov_b32 m0, s68
	v_lshl_add_u64 v[180:181], v[222:223], 0, s[10:11]
	global_load_lds_dwordx4 v[180:181], off
	s_waitcnt vmcnt(8)
	s_waitcnt lgkmcnt(0)
	s_setprio 1
	s_barrier
	v_mfma_f32_16x16x32_bf16 v[62:65], v[114:117], v[172:175], v[62:65]
	v_mfma_f32_16x16x32_bf16 v[58:61], v[122:125], v[172:175], v[58:61]
	v_mfma_f32_16x16x32_bf16 v[46:49], v[114:117], v[186:189], v[46:49]
	v_mfma_f32_16x16x32_bf16 v[42:45], v[122:125], v[186:189], v[42:45]
	v_mfma_f32_16x16x32_bf16 v[30:33], v[114:117], v[202:205], v[30:33]
	v_mfma_f32_16x16x32_bf16 v[26:29], v[122:125], v[202:205], v[26:29]
	v_mfma_f32_16x16x32_bf16 v[14:17], v[114:117], v[210:213], v[14:17]
	v_mfma_f32_16x16x32_bf16 v[10:13], v[122:125], v[210:213], v[10:13]
	v_mfma_f32_16x16x32_bf16 v[62:65], v[118:121], v[176:179], v[62:65]
	v_mfma_f32_16x16x32_bf16 v[58:61], v[134:137], v[176:179], v[58:61]
	v_mfma_f32_16x16x32_bf16 v[46:49], v[118:121], v[190:193], v[46:49]
	v_mfma_f32_16x16x32_bf16 v[42:45], v[134:137], v[190:193], v[42:45]
	v_mfma_f32_16x16x32_bf16 v[30:33], v[118:121], v[206:209], v[30:33]
	v_mfma_f32_16x16x32_bf16 v[26:29], v[134:137], v[206:209], v[26:29]
	v_mfma_f32_16x16x32_bf16 v[14:17], v[118:121], v[214:217], v[14:17]
	v_mfma_f32_16x16x32_bf16 v[10:13], v[134:137], v[214:217], v[10:13]
	v_mfma_f32_16x16x32_bf16 v[54:57], v[146:149], v[172:175], v[54:57]
	v_mfma_f32_16x16x32_bf16 v[50:53], v[164:167], v[172:175], v[50:53]
	v_mfma_f32_16x16x32_bf16 v[38:41], v[146:149], v[186:189], v[38:41]
	v_mfma_f32_16x16x32_bf16 v[34:37], v[164:167], v[186:189], v[34:37]
	v_mfma_f32_16x16x32_bf16 v[22:25], v[146:149], v[202:205], v[22:25]
	v_mfma_f32_16x16x32_bf16 v[18:21], v[164:167], v[202:205], v[18:21]
	v_mfma_f32_16x16x32_bf16 v[6:9], v[146:149], v[210:213], v[6:9]
	v_mfma_f32_16x16x32_bf16 v[2:5], v[164:167], v[210:213], v[2:5]
	v_mfma_f32_16x16x32_bf16 v[54:57], v[150:153], v[176:179], v[54:57]
	v_mfma_f32_16x16x32_bf16 v[50:53], v[168:171], v[176:179], v[50:53]
	v_mfma_f32_16x16x32_bf16 v[38:41], v[150:153], v[190:193], v[38:41]
	v_mfma_f32_16x16x32_bf16 v[34:37], v[168:171], v[190:193], v[34:37]
	v_mfma_f32_16x16x32_bf16 v[22:25], v[150:153], v[206:209], v[22:25]
	v_mfma_f32_16x16x32_bf16 v[18:21], v[168:171], v[206:209], v[18:21]
	v_mfma_f32_16x16x32_bf16 v[6:9], v[150:153], v[214:217], v[6:9]
	v_mfma_f32_16x16x32_bf16 v[2:5], v[168:171], v[214:217], v[2:5]
	s_barrier
	s_setprio 0
	s_cmp_gt_u32 s53, 61
	s_cbranch_scc0 .LBB0_626
	s_and_b64 vcc, exec, s[48:49]
	s_cbranch_vccz .LBB0_629
	s_barrier

.LBB0_711:
	s_add_i32 s29, s28, 2
	s_add_u32 s33, s14, 0x80
	s_addc_u32 s54, s15, 0
	s_add_i32 s72, 0, 0x10000
	s_cmp_eq_u32 s66, s28
	s_cselect_b32 s55, s5, s54
	s_cselect_b32 s54, s4, s33
	s_cselect_b32 s71, s13, s21
	s_cselect_b32 s70, s12, s20
	s_add_i32 s28, 0, 0x14000
	v_add_u32_e32 v156, s72, v141
	v_add_u32_e32 v172, s28, v141
	ds_read_b128 v[144:147], v156
	ds_read_b128 v[148:151], v156 offset:1024
	ds_read_b128 v[152:155], v156 offset:2048
	ds_read_b128 v[156:159], v156 offset:3072
	ds_read_b128 v[160:163], v172
	ds_read_b128 v[164:167], v172 offset:1024
	ds_read_b128 v[168:171], v172 offset:2048
	ds_read_b128 v[172:175], v172 offset:3072
	v_lshl_add_u64 v[192:193], s[14:15], 0, v[138:139]
	s_add_i32 m0, s59, 0xc000
	ds_read_b128 v[176:179], v143
	ds_read_b128 v[180:183], v143 offset:1024
	ds_read_b128 v[184:187], v143 offset:2048
	ds_read_b128 v[188:191], v143 offset:3072
	ds_read_b128 v[202:205], v143 offset:4096
	ds_read_b128 v[206:209], v143 offset:5120
	ds_read_b128 v[210:213], v143 offset:6144
	ds_read_b128 v[214:217], v143 offset:7168
	global_load_lds_dwordx4 v[192:193], off
	s_add_i32 m0, s59, 0xe000
	v_lshl_add_u64 v[192:193], s[14:15], 0, v[136:137]
	global_load_lds_dwordx4 v[192:193], off
	s_waitcnt vmcnt(8)
	s_waitcnt lgkmcnt(0)
	s_setprio 1
	s_barrier
	v_mfma_f32_16x16x32_bf16 v[122:125], v[144:147], v[176:179], v[122:125]
	v_mfma_f32_16x16x32_bf16 v[126:129], v[152:155], v[176:179], v[126:129]
	v_mfma_f32_16x16x32_bf16 v[110:113], v[144:147], v[184:187], v[110:113]
	v_mfma_f32_16x16x32_bf16 v[106:109], v[152:155], v[184:187], v[106:109]
	v_mfma_f32_16x16x32_bf16 v[94:97], v[144:147], v[202:205], v[94:97]
	v_mfma_f32_16x16x32_bf16 v[90:93], v[152:155], v[202:205], v[90:93]
	v_mfma_f32_16x16x32_bf16 v[78:81], v[144:147], v[210:213], v[78:81]
	v_mfma_f32_16x16x32_bf16 v[74:77], v[152:155], v[210:213], v[74:77]
	v_mfma_f32_16x16x32_bf16 v[122:125], v[148:151], v[180:183], v[122:125]
	v_mfma_f32_16x16x32_bf16 v[126:129], v[156:159], v[180:183], v[126:129]
	v_mfma_f32_16x16x32_bf16 v[110:113], v[148:151], v[188:191], v[110:113]
	v_mfma_f32_16x16x32_bf16 v[106:109], v[156:159], v[188:191], v[106:109]
	v_mfma_f32_16x16x32_bf16 v[94:97], v[148:151], v[206:209], v[94:97]
	v_mfma_f32_16x16x32_bf16 v[90:93], v[156:159], v[206:209], v[90:93]
	v_mfma_f32_16x16x32_bf16 v[78:81], v[148:151], v[214:217], v[78:81]
	v_mfma_f32_16x16x32_bf16 v[74:77], v[156:159], v[214:217], v[74:77]
	v_mfma_f32_16x16x32_bf16 v[118:121], v[160:163], v[176:179], v[118:121]
	v_mfma_f32_16x16x32_bf16 v[114:117], v[168:171], v[176:179], v[114:117]
	v_mfma_f32_16x16x32_bf16 v[102:105], v[160:163], v[184:187], v[102:105]
	v_mfma_f32_16x16x32_bf16 v[98:101], v[168:171], v[184:187], v[98:101]
	v_mfma_f32_16x16x32_bf16 v[86:89], v[160:163], v[202:205], v[86:89]
	v_mfma_f32_16x16x32_bf16 v[82:85], v[168:171], v[202:205], v[82:85]
	v_mfma_f32_16x16x32_bf16 v[70:73], v[160:163], v[210:213], v[70:73]
	v_mfma_f32_16x16x32_bf16 v[66:69], v[168:171], v[210:213], v[66:69]
	v_mfma_f32_16x16x32_bf16 v[118:121], v[164:167], v[180:183], v[118:121]
	v_mfma_f32_16x16x32_bf16 v[114:117], v[172:175], v[180:183], v[114:117]
	v_mfma_f32_16x16x32_bf16 v[102:105], v[164:167], v[188:191], v[102:105]
	v_mfma_f32_16x16x32_bf16 v[98:101], v[172:175], v[188:191], v[98:101]
	v_mfma_f32_16x16x32_bf16 v[86:89], v[164:167], v[206:209], v[86:89]
	v_mfma_f32_16x16x32_bf16 v[82:85], v[172:175], v[206:209], v[82:85]
	v_mfma_f32_16x16x32_bf16 v[70:73], v[164:167], v[214:217], v[70:73]
	v_mfma_f32_16x16x32_bf16 v[66:69], v[172:175], v[214:217], v[66:69]
	s_barrier
	s_setprio 0
	s_add_i32 s33, s72, s58
	v_lshl_add_u64 v[192:193], s[70:71], 0, v[0:1]
	s_mov_b32 m0, s33
	ds_read_b128 v[176:179], v143 offset:16384
	ds_read_b128 v[180:183], v143 offset:17408
	ds_read_b128 v[184:187], v143 offset:18432
	ds_read_b128 v[188:191], v143 offset:19456
	ds_read_b128 v[202:205], v143 offset:20480
	ds_read_b128 v[206:209], v143 offset:21504
	ds_read_b128 v[210:213], v143 offset:22528
	ds_read_b128 v[214:217], v143 offset:23552
	global_load_lds_dwordx4 v[192:193], off
	s_add_i32 m0, s33, 0x2000
	v_lshl_add_u64 v[218:219], s[70:71], 0, v[130:131]
	s_add_u32 s70, s70, s42
	s_addc_u32 s71, s71, s43
	s_add_i32 s28, s28, s58
	global_load_lds_dwordx4 v[218:219], off
	v_lshl_add_u64 v[220:221], s[70:71], 0, v[0:1]
	s_mov_b32 m0, s28
	v_lshl_add_u64 v[222:223], s[70:71], 0, v[130:131]
	global_load_lds_dwordx4 v[220:221], off
	s_add_i32 m0, s28, 0x2000
	v_lshl_add_u64 v[232:233], s[54:55], 0, v[134:135]
	global_load_lds_dwordx4 v[222:223], off
	s_mov_b32 m0, s59
	v_lshl_add_u64 v[234:235], s[54:55], 0, v[132:133]
	global_load_lds_dwordx4 v[232:233], off
	s_mov_b32 m0, s60
	s_nop 0
	global_load_lds_dwordx4 v[234:235], off
	s_waitcnt vmcnt(8)
	s_waitcnt lgkmcnt(0)
	s_setprio 1
	s_barrier
	v_mfma_f32_16x16x32_bf16 v[62:65], v[144:147], v[176:179], v[62:65]
	v_mfma_f32_16x16x32_bf16 v[58:61], v[152:155], v[176:179], v[58:61]
	v_mfma_f32_16x16x32_bf16 v[46:49], v[144:147], v[184:187], v[46:49]
	v_mfma_f32_16x16x32_bf16 v[42:45], v[152:155], v[184:187], v[42:45]
	v_mfma_f32_16x16x32_bf16 v[30:33], v[144:147], v[202:205], v[30:33]
	v_mfma_f32_16x16x32_bf16 v[26:29], v[152:155], v[202:205], v[26:29]
	v_mfma_f32_16x16x32_bf16 v[14:17], v[144:147], v[210:213], v[14:17]
	v_mfma_f32_16x16x32_bf16 v[10:13], v[152:155], v[210:213], v[10:13]
	v_mfma_f32_16x16x32_bf16 v[62:65], v[148:151], v[180:183], v[62:65]
	v_mfma_f32_16x16x32_bf16 v[58:61], v[156:159], v[180:183], v[58:61]
	v_mfma_f32_16x16x32_bf16 v[46:49], v[148:151], v[188:191], v[46:49]
	v_mfma_f32_16x16x32_bf16 v[42:45], v[156:159], v[188:191], v[42:45]
	v_mfma_f32_16x16x32_bf16 v[30:33], v[148:151], v[206:209], v[30:33]
	v_mfma_f32_16x16x32_bf16 v[26:29], v[156:159], v[206:209], v[26:29]
	v_mfma_f32_16x16x32_bf16 v[14:17], v[148:151], v[214:217], v[14:17]
	v_mfma_f32_16x16x32_bf16 v[10:13], v[156:159], v[214:217], v[10:13]
	v_mfma_f32_16x16x32_bf16 v[54:57], v[160:163], v[176:179], v[54:57]
	v_mfma_f32_16x16x32_bf16 v[50:53], v[168:171], v[176:179], v[50:53]
	v_mfma_f32_16x16x32_bf16 v[38:41], v[160:163], v[184:187], v[38:41]
	v_mfma_f32_16x16x32_bf16 v[34:37], v[168:171], v[184:187], v[34:37]
	v_mfma_f32_16x16x32_bf16 v[22:25], v[160:163], v[202:205], v[22:25]
	v_mfma_f32_16x16x32_bf16 v[18:21], v[168:171], v[202:205], v[18:21]
	v_mfma_f32_16x16x32_bf16 v[6:9], v[160:163], v[210:213], v[6:9]
	v_mfma_f32_16x16x32_bf16 v[2:5], v[168:171], v[210:213], v[2:5]
	v_mfma_f32_16x16x32_bf16 v[54:57], v[164:167], v[180:183], v[54:57]
	v_mfma_f32_16x16x32_bf16 v[50:53], v[172:175], v[180:183], v[50:53]
	v_mfma_f32_16x16x32_bf16 v[38:41], v[164:167], v[188:191], v[38:41]
	v_mfma_f32_16x16x32_bf16 v[34:37], v[172:175], v[188:191], v[34:37]
	v_mfma_f32_16x16x32_bf16 v[22:25], v[164:167], v[206:209], v[22:25]
	v_mfma_f32_16x16x32_bf16 v[18:21], v[172:175], v[206:209], v[18:21]
	v_mfma_f32_16x16x32_bf16 v[6:9], v[164:167], v[214:217], v[6:9]
	v_mfma_f32_16x16x32_bf16 v[2:5], v[172:175], v[214:217], v[2:5]
	s_barrier
	s_setprio 0
	s_add_i32 s28, 0, 0x18000
	s_add_i32 s33, 0, 0x1c000
	v_add_u32_e32 v156, s28, v141
	v_add_u32_e32 v172, s33, v141
	ds_read_b128 v[144:147], v156
	ds_read_b128 v[148:151], v156 offset:1024
	ds_read_b128 v[152:155], v156 offset:2048
	ds_read_b128 v[156:159], v156 offset:3072
	ds_read_b128 v[160:163], v172
	ds_read_b128 v[164:167], v172 offset:1024
	ds_read_b128 v[168:171], v172 offset:2048
	ds_read_b128 v[172:175], v172 offset:3072
	s_add_u32 s54, s54, s42
	s_addc_u32 s55, s55, s43
	s_mov_b32 m0, s61
	v_lshl_add_u64 v[236:237], s[54:55], 0, v[134:135]
	ds_read_b128 v[176:179], v143 offset:32768
	ds_read_b128 v[180:183], v143 offset:33792
	ds_read_b128 v[184:187], v143 offset:34816
	ds_read_b128 v[188:191], v143 offset:35840
	ds_read_b128 v[202:205], v143 offset:36864
	ds_read_b128 v[206:209], v143 offset:37888
	ds_read_b128 v[210:213], v143 offset:38912
	ds_read_b128 v[214:217], v143 offset:39936
	global_load_lds_dwordx4 v[236:237], off
	s_mov_b32 m0, s62
	v_lshl_add_u64 v[236:237], s[54:55], 0, v[132:133]
	global_load_lds_dwordx4 v[236:237], off
	s_waitcnt vmcnt(8)
	s_waitcnt lgkmcnt(0)
	s_setprio 1
	s_barrier
	v_mfma_f32_16x16x32_bf16 v[122:125], v[144:147], v[176:179], v[122:125]
	v_mfma_f32_16x16x32_bf16 v[126:129], v[152:155], v[176:179], v[126:129]
	v_mfma_f32_16x16x32_bf16 v[110:113], v[144:147], v[184:187], v[110:113]
	v_mfma_f32_16x16x32_bf16 v[106:109], v[152:155], v[184:187], v[106:109]
	v_mfma_f32_16x16x32_bf16 v[94:97], v[144:147], v[202:205], v[94:97]
	v_mfma_f32_16x16x32_bf16 v[90:93], v[152:155], v[202:205], v[90:93]
	v_mfma_f32_16x16x32_bf16 v[78:81], v[144:147], v[210:213], v[78:81]
	v_mfma_f32_16x16x32_bf16 v[74:77], v[152:155], v[210:213], v[74:77]
	v_mfma_f32_16x16x32_bf16 v[122:125], v[148:151], v[180:183], v[122:125]
	v_mfma_f32_16x16x32_bf16 v[126:129], v[156:159], v[180:183], v[126:129]
	v_mfma_f32_16x16x32_bf16 v[110:113], v[148:151], v[188:191], v[110:113]
	v_mfma_f32_16x16x32_bf16 v[106:109], v[156:159], v[188:191], v[106:109]
	v_mfma_f32_16x16x32_bf16 v[94:97], v[148:151], v[206:209], v[94:97]
	v_mfma_f32_16x16x32_bf16 v[90:93], v[156:159], v[206:209], v[90:93]
	v_mfma_f32_16x16x32_bf16 v[78:81], v[148:151], v[214:217], v[78:81]
	v_mfma_f32_16x16x32_bf16 v[74:77], v[156:159], v[214:217], v[74:77]
	v_mfma_f32_16x16x32_bf16 v[118:121], v[160:163], v[176:179], v[118:121]
	v_mfma_f32_16x16x32_bf16 v[114:117], v[168:171], v[176:179], v[114:117]
	v_mfma_f32_16x16x32_bf16 v[102:105], v[160:163], v[184:187], v[102:105]
	v_mfma_f32_16x16x32_bf16 v[98:101], v[168:171], v[184:187], v[98:101]
	v_mfma_f32_16x16x32_bf16 v[86:89], v[160:163], v[202:205], v[86:89]
	v_mfma_f32_16x16x32_bf16 v[82:85], v[168:171], v[202:205], v[82:85]
	v_mfma_f32_16x16x32_bf16 v[70:73], v[160:163], v[210:213], v[70:73]
	v_mfma_f32_16x16x32_bf16 v[66:69], v[168:171], v[210:213], v[66:69]
	v_mfma_f32_16x16x32_bf16 v[118:121], v[164:167], v[180:183], v[118:121]
	v_mfma_f32_16x16x32_bf16 v[114:117], v[172:175], v[180:183], v[114:117]
	v_mfma_f32_16x16x32_bf16 v[102:105], v[164:167], v[188:191], v[102:105]
	v_mfma_f32_16x16x32_bf16 v[98:101], v[172:175], v[188:191], v[98:101]
	v_mfma_f32_16x16x32_bf16 v[86:89], v[164:167], v[206:209], v[86:89]
	v_mfma_f32_16x16x32_bf16 v[82:85], v[172:175], v[206:209], v[82:85]
	v_mfma_f32_16x16x32_bf16 v[70:73], v[164:167], v[214:217], v[70:73]
	v_mfma_f32_16x16x32_bf16 v[66:69], v[172:175], v[214:217], v[66:69]
	s_barrier
	s_setprio 0
	s_add_i32 s28, s28, s58
	v_lshl_add_u64 v[192:193], v[192:193], 0, s[10:11]
	s_mov_b32 m0, s28
	ds_read_b128 v[176:179], v143 offset:49152
	ds_read_b128 v[180:183], v143 offset:50176
	ds_read_b128 v[184:187], v143 offset:51200
	ds_read_b128 v[188:191], v143 offset:52224
	ds_read_b128 v[202:205], v143 offset:53248
	ds_read_b128 v[206:209], v143 offset:54272
	ds_read_b128 v[210:213], v143 offset:55296
	ds_read_b128 v[214:217], v143 offset:56320
	global_load_lds_dwordx4 v[192:193], off
	v_lshl_add_u64 v[192:193], v[218:219], 0, s[10:11]
	s_add_i32 m0, s28, 0x2000
	s_add_i32 s28, s33, s58
	global_load_lds_dwordx4 v[192:193], off
	s_mov_b32 m0, s28
	v_lshl_add_u64 v[192:193], v[220:221], 0, s[10:11]
	global_load_lds_dwordx4 v[192:193], off
	s_add_i32 m0, s28, 0x2000
	v_lshl_add_u64 v[192:193], v[222:223], 0, s[10:11]
	global_load_lds_dwordx4 v[192:193], off
	s_mov_b32 m0, s64
	v_lshl_add_u64 v[192:193], v[232:233], 0, s[10:11]
	global_load_lds_dwordx4 v[192:193], off
	s_mov_b32 m0, s65
	v_lshl_add_u64 v[192:193], v[234:235], 0, s[10:11]
	global_load_lds_dwordx4 v[192:193], off
	s_waitcnt vmcnt(8)
	s_waitcnt lgkmcnt(0)
	s_setprio 1
	s_barrier
	v_mfma_f32_16x16x32_bf16 v[62:65], v[144:147], v[176:179], v[62:65]
	v_mfma_f32_16x16x32_bf16 v[58:61], v[152:155], v[176:179], v[58:61]
	v_mfma_f32_16x16x32_bf16 v[46:49], v[144:147], v[184:187], v[46:49]
	v_mfma_f32_16x16x32_bf16 v[42:45], v[152:155], v[184:187], v[42:45]
	v_mfma_f32_16x16x32_bf16 v[30:33], v[144:147], v[202:205], v[30:33]
	v_mfma_f32_16x16x32_bf16 v[26:29], v[152:155], v[202:205], v[26:29]
	v_mfma_f32_16x16x32_bf16 v[14:17], v[144:147], v[210:213], v[14:17]
	v_mfma_f32_16x16x32_bf16 v[10:13], v[152:155], v[210:213], v[10:13]
	v_mfma_f32_16x16x32_bf16 v[62:65], v[148:151], v[180:183], v[62:65]
	v_mfma_f32_16x16x32_bf16 v[58:61], v[156:159], v[180:183], v[58:61]
	v_mfma_f32_16x16x32_bf16 v[46:49], v[148:151], v[188:191], v[46:49]
	v_mfma_f32_16x16x32_bf16 v[42:45], v[156:159], v[188:191], v[42:45]
	v_mfma_f32_16x16x32_bf16 v[30:33], v[148:151], v[206:209], v[30:33]
	v_mfma_f32_16x16x32_bf16 v[26:29], v[156:159], v[206:209], v[26:29]
	v_mfma_f32_16x16x32_bf16 v[14:17], v[148:151], v[214:217], v[14:17]
	v_mfma_f32_16x16x32_bf16 v[10:13], v[156:159], v[214:217], v[10:13]
	v_mfma_f32_16x16x32_bf16 v[54:57], v[160:163], v[176:179], v[54:57]
	v_mfma_f32_16x16x32_bf16 v[50:53], v[168:171], v[176:179], v[50:53]
	v_mfma_f32_16x16x32_bf16 v[38:41], v[160:163], v[184:187], v[38:41]
	v_mfma_f32_16x16x32_bf16 v[34:37], v[168:171], v[184:187], v[34:37]
	v_mfma_f32_16x16x32_bf16 v[22:25], v[160:163], v[202:205], v[22:25]
	v_mfma_f32_16x16x32_bf16 v[18:21], v[168:171], v[202:205], v[18:21]
	v_mfma_f32_16x16x32_bf16 v[6:9], v[160:163], v[210:213], v[6:9]
	v_mfma_f32_16x16x32_bf16 v[2:5], v[168:171], v[210:213], v[2:5]
	v_mfma_f32_16x16x32_bf16 v[54:57], v[164:167], v[180:183], v[54:57]
	v_mfma_f32_16x16x32_bf16 v[50:53], v[172:175], v[180:183], v[50:53]
	v_mfma_f32_16x16x32_bf16 v[38:41], v[164:167], v[188:191], v[38:41]
	v_mfma_f32_16x16x32_bf16 v[34:37], v[172:175], v[188:191], v[34:37]
	v_mfma_f32_16x16x32_bf16 v[22:25], v[164:167], v[206:209], v[22:25]
	v_mfma_f32_16x16x32_bf16 v[18:21], v[172:175], v[206:209], v[18:21]
	v_mfma_f32_16x16x32_bf16 v[6:9], v[164:167], v[214:217], v[6:9]
	v_mfma_f32_16x16x32_bf16 v[2:5], v[172:175], v[214:217], v[2:5]
	s_barrier
	s_setprio 0
	s_add_u32 s20, s20, 0x100
	s_addc_u32 s21, s21, 0
	s_add_u32 s14, s14, 0x100
	s_addc_u32 s15, s15, 0
	s_cmp_ge_i32 s29, s63
	s_mov_b32 s28, s29
	s_cbranch_scc0 .LBB0_711

.LBB0_731:
	s_add_u32 s37, s14, 0xfffc0080
	s_addc_u32 s51, s15, -1
	s_add_i32 s53, 0, 0x10000
	s_cmp_eq_u32 s36, 12
	s_cselect_b32 s63, s13, s51
	s_cselect_b32 s62, s20, s37
	s_cselect_b32 s61, s21, s33
	s_cselect_b32 s60, s28, s29
	s_add_i32 s37, 0, 0x14000
	v_add_u32_e32 v142, s53, v232
	v_add_u32_e32 v158, s37, v232
	ds_read_b128 v[126:129], v142
	ds_read_b128 v[134:137], v142 offset:1024
	ds_read_b128 v[138:141], v142 offset:2048
	ds_read_b128 v[142:145], v142 offset:3072
	ds_read_b128 v[146:149], v158
	ds_read_b128 v[150:153], v158 offset:1024
	ds_read_b128 v[154:157], v158 offset:2048
	ds_read_b128 v[158:161], v158 offset:3072
	v_lshl_add_u64 v[212:213], s[14:15], 0, v[210:211]
	s_add_i32 m0, s59, 0xc000
	ds_read_b128 v[162:165], v234
	ds_read_b128 v[166:169], v234 offset:1024
	ds_read_b128 v[170:173], v234 offset:2048
	ds_read_b128 v[174:177], v234 offset:3072
	ds_read_b128 v[178:181], v234 offset:4096
	ds_read_b128 v[182:185], v234 offset:5120
	ds_read_b128 v[186:189], v234 offset:6144
	ds_read_b128 v[190:193], v234 offset:7168
	global_load_lds_dwordx4 v[212:213], off
	s_add_i32 m0, s59, 0xe000
	v_lshl_add_u64 v[212:213], s[14:15], 0, v[208:209]
	global_load_lds_dwordx4 v[212:213], off
	s_waitcnt vmcnt(8)
	s_waitcnt lgkmcnt(0)
	s_setprio 1
	s_barrier
	v_mfma_f32_16x16x32_bf16 v[130:133], v[126:129], v[162:165], v[130:133]
	v_mfma_f32_16x16x32_bf16 v[122:125], v[138:141], v[162:165], v[122:125]
	v_mfma_f32_16x16x32_bf16 v[110:113], v[126:129], v[170:173], v[110:113]
	v_mfma_f32_16x16x32_bf16 v[106:109], v[138:141], v[170:173], v[106:109]
	v_mfma_f32_16x16x32_bf16 v[94:97], v[126:129], v[178:181], v[94:97]
	v_mfma_f32_16x16x32_bf16 v[90:93], v[138:141], v[178:181], v[90:93]
	v_mfma_f32_16x16x32_bf16 v[78:81], v[126:129], v[186:189], v[78:81]
	v_mfma_f32_16x16x32_bf16 v[74:77], v[138:141], v[186:189], v[74:77]
	v_mfma_f32_16x16x32_bf16 v[130:133], v[134:137], v[166:169], v[130:133]
	v_mfma_f32_16x16x32_bf16 v[122:125], v[142:145], v[166:169], v[122:125]
	v_mfma_f32_16x16x32_bf16 v[110:113], v[134:137], v[174:177], v[110:113]
	v_mfma_f32_16x16x32_bf16 v[106:109], v[142:145], v[174:177], v[106:109]
	v_mfma_f32_16x16x32_bf16 v[94:97], v[134:137], v[182:185], v[94:97]
	v_mfma_f32_16x16x32_bf16 v[90:93], v[142:145], v[182:185], v[90:93]
	v_mfma_f32_16x16x32_bf16 v[78:81], v[134:137], v[190:193], v[78:81]
	v_mfma_f32_16x16x32_bf16 v[74:77], v[142:145], v[190:193], v[74:77]
	v_mfma_f32_16x16x32_bf16 v[118:121], v[146:149], v[162:165], v[118:121]
	v_mfma_f32_16x16x32_bf16 v[114:117], v[154:157], v[162:165], v[114:117]
	v_mfma_f32_16x16x32_bf16 v[102:105], v[146:149], v[170:173], v[102:105]
	v_mfma_f32_16x16x32_bf16 v[98:101], v[154:157], v[170:173], v[98:101]
	v_mfma_f32_16x16x32_bf16 v[86:89], v[146:149], v[178:181], v[86:89]
	v_mfma_f32_16x16x32_bf16 v[82:85], v[154:157], v[178:181], v[82:85]
	v_mfma_f32_16x16x32_bf16 v[70:73], v[146:149], v[186:189], v[70:73]
	v_mfma_f32_16x16x32_bf16 v[66:69], v[154:157], v[186:189], v[66:69]
	v_mfma_f32_16x16x32_bf16 v[118:121], v[150:153], v[166:169], v[118:121]
	v_mfma_f32_16x16x32_bf16 v[114:117], v[158:161], v[166:169], v[114:117]
	v_mfma_f32_16x16x32_bf16 v[102:105], v[150:153], v[174:177], v[102:105]
	v_mfma_f32_16x16x32_bf16 v[98:101], v[158:161], v[174:177], v[98:101]
	v_mfma_f32_16x16x32_bf16 v[86:89], v[150:153], v[182:185], v[86:89]
	v_mfma_f32_16x16x32_bf16 v[82:85], v[158:161], v[182:185], v[82:85]
	v_mfma_f32_16x16x32_bf16 v[70:73], v[150:153], v[190:193], v[70:73]
	v_mfma_f32_16x16x32_bf16 v[66:69], v[158:161], v[190:193], v[66:69]
	s_barrier
	s_setprio 0
	s_add_i32 s51, s53, s66
	v_lshl_add_u64 v[212:213], s[60:61], 0, v[0:1]
	s_mov_b32 m0, s51
	ds_read_b128 v[162:165], v234 offset:16384
	ds_read_b128 v[166:169], v234 offset:17408
	ds_read_b128 v[170:173], v234 offset:18432
	ds_read_b128 v[174:177], v234 offset:19456
	ds_read_b128 v[178:181], v234 offset:20480
	ds_read_b128 v[182:185], v234 offset:21504
	ds_read_b128 v[186:189], v234 offset:22528
	ds_read_b128 v[190:193], v234 offset:23552
	global_load_lds_dwordx4 v[212:213], off
	s_add_i32 m0, s51, 0x2000
	s_add_u32 s74, s60, 0x40000
	v_lshl_add_u64 v[214:215], s[60:61], 0, v[202:203]
	s_addc_u32 s75, s61, 0
	s_add_i32 s37, s37, s66
	global_load_lds_dwordx4 v[214:215], off
	v_lshl_add_u64 v[216:217], s[74:75], 0, v[0:1]
	s_mov_b32 m0, s37
	v_lshl_add_u64 v[218:219], s[62:63], 0, v[204:205]
	global_load_lds_dwordx4 v[216:217], off
	s_add_i32 m0, s37, 0x2000
	v_lshl_add_u64 v[216:217], s[74:75], 0, v[202:203]
	global_load_lds_dwordx4 v[216:217], off
	s_mov_b32 m0, s59
	v_lshl_add_u64 v[216:217], s[62:63], 0, v[206:207]
	global_load_lds_dwordx4 v[216:217], off
	s_mov_b32 m0, s67
	s_nop 0
	global_load_lds_dwordx4 v[218:219], off
	s_waitcnt vmcnt(8)
	s_waitcnt lgkmcnt(0)
	s_setprio 1
	s_barrier
	v_mfma_f32_16x16x32_bf16 v[62:65], v[126:129], v[162:165], v[62:65]
	v_mfma_f32_16x16x32_bf16 v[58:61], v[138:141], v[162:165], v[58:61]
	v_mfma_f32_16x16x32_bf16 v[46:49], v[126:129], v[170:173], v[46:49]
	v_mfma_f32_16x16x32_bf16 v[42:45], v[138:141], v[170:173], v[42:45]
	v_mfma_f32_16x16x32_bf16 v[30:33], v[126:129], v[178:181], v[30:33]
	v_mfma_f32_16x16x32_bf16 v[26:29], v[138:141], v[178:181], v[26:29]
	v_mfma_f32_16x16x32_bf16 v[14:17], v[126:129], v[186:189], v[14:17]
	v_mfma_f32_16x16x32_bf16 v[10:13], v[138:141], v[186:189], v[10:13]
	v_mfma_f32_16x16x32_bf16 v[62:65], v[134:137], v[166:169], v[62:65]
	v_mfma_f32_16x16x32_bf16 v[58:61], v[142:145], v[166:169], v[58:61]
	v_mfma_f32_16x16x32_bf16 v[46:49], v[134:137], v[174:177], v[46:49]
	v_mfma_f32_16x16x32_bf16 v[42:45], v[142:145], v[174:177], v[42:45]
	v_mfma_f32_16x16x32_bf16 v[30:33], v[134:137], v[182:185], v[30:33]
	v_mfma_f32_16x16x32_bf16 v[26:29], v[142:145], v[182:185], v[26:29]
	v_mfma_f32_16x16x32_bf16 v[14:17], v[134:137], v[190:193], v[14:17]
	v_mfma_f32_16x16x32_bf16 v[10:13], v[142:145], v[190:193], v[10:13]
	v_mfma_f32_16x16x32_bf16 v[54:57], v[146:149], v[162:165], v[54:57]
	v_mfma_f32_16x16x32_bf16 v[50:53], v[154:157], v[162:165], v[50:53]
	v_mfma_f32_16x16x32_bf16 v[38:41], v[146:149], v[170:173], v[38:41]
	v_mfma_f32_16x16x32_bf16 v[34:37], v[154:157], v[170:173], v[34:37]
	v_mfma_f32_16x16x32_bf16 v[22:25], v[146:149], v[178:181], v[22:25]
	v_mfma_f32_16x16x32_bf16 v[18:21], v[154:157], v[178:181], v[18:21]
	v_mfma_f32_16x16x32_bf16 v[6:9], v[146:149], v[186:189], v[6:9]
	v_mfma_f32_16x16x32_bf16 v[2:5], v[154:157], v[186:189], v[2:5]
	v_mfma_f32_16x16x32_bf16 v[54:57], v[150:153], v[166:169], v[54:57]
	v_mfma_f32_16x16x32_bf16 v[50:53], v[158:161], v[166:169], v[50:53]
	v_mfma_f32_16x16x32_bf16 v[38:41], v[150:153], v[174:177], v[38:41]
	v_mfma_f32_16x16x32_bf16 v[34:37], v[158:161], v[174:177], v[34:37]
	v_mfma_f32_16x16x32_bf16 v[22:25], v[150:153], v[182:185], v[22:25]
	v_mfma_f32_16x16x32_bf16 v[18:21], v[158:161], v[182:185], v[18:21]
	v_mfma_f32_16x16x32_bf16 v[6:9], v[150:153], v[190:193], v[6:9]
	v_mfma_f32_16x16x32_bf16 v[2:5], v[158:161], v[190:193], v[2:5]
	s_barrier
	s_setprio 0
	s_add_i32 s37, 0, 0x18000
	s_add_i32 s51, 0, 0x1c000
	v_add_u32_e32 v142, s37, v232
	v_add_u32_e32 v158, s51, v232
	ds_read_b128 v[126:129], v142
	ds_read_b128 v[134:137], v142 offset:1024
	ds_read_b128 v[138:141], v142 offset:2048
	ds_read_b128 v[142:145], v142 offset:3072
	ds_read_b128 v[146:149], v158
	ds_read_b128 v[150:153], v158 offset:1024
	ds_read_b128 v[154:157], v158 offset:2048
	ds_read_b128 v[158:161], v158 offset:3072
	s_add_u32 s62, s62, 0x40000
	s_addc_u32 s63, s63, 0
	s_mov_b32 m0, s68
	v_lshl_add_u64 v[220:221], s[62:63], 0, v[206:207]
	ds_read_b128 v[162:165], v234 offset:32768
	ds_read_b128 v[166:169], v234 offset:33792
	ds_read_b128 v[170:173], v234 offset:34816
	ds_read_b128 v[174:177], v234 offset:35840
	ds_read_b128 v[178:181], v234 offset:36864
	ds_read_b128 v[182:185], v234 offset:37888
	ds_read_b128 v[186:189], v234 offset:38912
	ds_read_b128 v[190:193], v234 offset:39936
	global_load_lds_dwordx4 v[220:221], off
	s_mov_b32 m0, s69
	v_lshl_add_u64 v[220:221], s[62:63], 0, v[204:205]
	global_load_lds_dwordx4 v[220:221], off
	s_waitcnt vmcnt(8)
	s_waitcnt lgkmcnt(0)
	s_setprio 1
	s_barrier
	v_mfma_f32_16x16x32_bf16 v[130:133], v[126:129], v[162:165], v[130:133]
	v_mfma_f32_16x16x32_bf16 v[122:125], v[138:141], v[162:165], v[122:125]
	v_mfma_f32_16x16x32_bf16 v[110:113], v[126:129], v[170:173], v[110:113]
	v_mfma_f32_16x16x32_bf16 v[106:109], v[138:141], v[170:173], v[106:109]
	v_mfma_f32_16x16x32_bf16 v[94:97], v[126:129], v[178:181], v[94:97]
	v_mfma_f32_16x16x32_bf16 v[90:93], v[138:141], v[178:181], v[90:93]
	v_mfma_f32_16x16x32_bf16 v[78:81], v[126:129], v[186:189], v[78:81]
	v_mfma_f32_16x16x32_bf16 v[74:77], v[138:141], v[186:189], v[74:77]
	v_mfma_f32_16x16x32_bf16 v[130:133], v[134:137], v[166:169], v[130:133]
	v_mfma_f32_16x16x32_bf16 v[122:125], v[142:145], v[166:169], v[122:125]
	v_mfma_f32_16x16x32_bf16 v[110:113], v[134:137], v[174:177], v[110:113]
	v_mfma_f32_16x16x32_bf16 v[106:109], v[142:145], v[174:177], v[106:109]
	v_mfma_f32_16x16x32_bf16 v[94:97], v[134:137], v[182:185], v[94:97]
	v_mfma_f32_16x16x32_bf16 v[90:93], v[142:145], v[182:185], v[90:93]
	v_mfma_f32_16x16x32_bf16 v[78:81], v[134:137], v[190:193], v[78:81]
	v_mfma_f32_16x16x32_bf16 v[74:77], v[142:145], v[190:193], v[74:77]
	v_mfma_f32_16x16x32_bf16 v[118:121], v[146:149], v[162:165], v[118:121]
	v_mfma_f32_16x16x32_bf16 v[114:117], v[154:157], v[162:165], v[114:117]
	v_mfma_f32_16x16x32_bf16 v[102:105], v[146:149], v[170:173], v[102:105]
	v_mfma_f32_16x16x32_bf16 v[98:101], v[154:157], v[170:173], v[98:101]
	v_mfma_f32_16x16x32_bf16 v[86:89], v[146:149], v[178:181], v[86:89]
	v_mfma_f32_16x16x32_bf16 v[82:85], v[154:157], v[178:181], v[82:85]
	v_mfma_f32_16x16x32_bf16 v[70:73], v[146:149], v[186:189], v[70:73]
	v_mfma_f32_16x16x32_bf16 v[66:69], v[154:157], v[186:189], v[66:69]
	v_mfma_f32_16x16x32_bf16 v[118:121], v[150:153], v[166:169], v[118:121]
	v_mfma_f32_16x16x32_bf16 v[114:117], v[158:161], v[166:169], v[114:117]
	v_mfma_f32_16x16x32_bf16 v[102:105], v[150:153], v[174:177], v[102:105]
	v_mfma_f32_16x16x32_bf16 v[98:101], v[158:161], v[174:177], v[98:101]
	v_mfma_f32_16x16x32_bf16 v[86:89], v[150:153], v[182:185], v[86:89]
	v_mfma_f32_16x16x32_bf16 v[82:85], v[158:161], v[182:185], v[82:85]
	v_mfma_f32_16x16x32_bf16 v[70:73], v[150:153], v[190:193], v[70:73]
	v_mfma_f32_16x16x32_bf16 v[66:69], v[158:161], v[190:193], v[66:69]
	s_barrier
	s_setprio 0
	s_add_i32 s37, s37, s66
	v_lshl_add_u64 v[212:213], v[212:213], 0, s[10:11]
	s_mov_b32 m0, s37
	ds_read_b128 v[162:165], v234 offset:49152
	ds_read_b128 v[166:169], v234 offset:50176
	ds_read_b128 v[170:173], v234 offset:51200
	ds_read_b128 v[174:177], v234 offset:52224
	ds_read_b128 v[178:181], v234 offset:53248
	ds_read_b128 v[182:185], v234 offset:54272
	ds_read_b128 v[186:189], v234 offset:55296
	ds_read_b128 v[190:193], v234 offset:56320
	s_add_i32 s36, s36, 2
	s_add_u32 s29, s29, 0x100
	s_addc_u32 s33, s33, 0
	s_add_u32 s14, s14, 0x100
	s_addc_u32 s15, s15, 0
	global_load_lds_dwordx4 v[212:213], off
	s_add_i32 m0, s37, 0x2000
	s_add_u32 s60, s60, 0x40080
	v_lshl_add_u64 v[212:213], v[214:215], 0, s[10:11]
	s_addc_u32 s61, s61, 0
	s_add_i32 s37, s51, s66
	global_load_lds_dwordx4 v[212:213], off
	s_mov_b32 m0, s37
	v_lshl_add_u64 v[212:213], s[60:61], 0, v[0:1]
	global_load_lds_dwordx4 v[212:213], off
	s_add_i32 m0, s37, 0x2000
	v_lshl_add_u64 v[212:213], s[60:61], 0, v[202:203]
	global_load_lds_dwordx4 v[212:213], off
	s_mov_b32 m0, s70
	v_lshl_add_u64 v[212:213], v[216:217], 0, s[10:11]
	global_load_lds_dwordx4 v[212:213], off
	s_mov_b32 m0, s71
	v_lshl_add_u64 v[212:213], v[218:219], 0, s[10:11]
	global_load_lds_dwordx4 v[212:213], off
	s_waitcnt vmcnt(8)
	s_waitcnt lgkmcnt(0)
	s_setprio 1
	s_barrier
	v_mfma_f32_16x16x32_bf16 v[62:65], v[126:129], v[162:165], v[62:65]
	v_mfma_f32_16x16x32_bf16 v[58:61], v[138:141], v[162:165], v[58:61]
	v_mfma_f32_16x16x32_bf16 v[46:49], v[126:129], v[170:173], v[46:49]
	v_mfma_f32_16x16x32_bf16 v[42:45], v[138:141], v[170:173], v[42:45]
	v_mfma_f32_16x16x32_bf16 v[30:33], v[126:129], v[178:181], v[30:33]
	v_mfma_f32_16x16x32_bf16 v[26:29], v[138:141], v[178:181], v[26:29]
	v_mfma_f32_16x16x32_bf16 v[14:17], v[126:129], v[186:189], v[14:17]
	v_mfma_f32_16x16x32_bf16 v[10:13], v[138:141], v[186:189], v[10:13]
	v_mfma_f32_16x16x32_bf16 v[62:65], v[134:137], v[166:169], v[62:65]
	v_mfma_f32_16x16x32_bf16 v[58:61], v[142:145], v[166:169], v[58:61]
	v_mfma_f32_16x16x32_bf16 v[46:49], v[134:137], v[174:177], v[46:49]
	v_mfma_f32_16x16x32_bf16 v[42:45], v[142:145], v[174:177], v[42:45]
	v_mfma_f32_16x16x32_bf16 v[30:33], v[134:137], v[182:185], v[30:33]
	v_mfma_f32_16x16x32_bf16 v[26:29], v[142:145], v[182:185], v[26:29]
	v_mfma_f32_16x16x32_bf16 v[14:17], v[134:137], v[190:193], v[14:17]
	v_mfma_f32_16x16x32_bf16 v[10:13], v[142:145], v[190:193], v[10:13]
	v_mfma_f32_16x16x32_bf16 v[54:57], v[146:149], v[162:165], v[54:57]
	v_mfma_f32_16x16x32_bf16 v[50:53], v[154:157], v[162:165], v[50:53]
	v_mfma_f32_16x16x32_bf16 v[38:41], v[146:149], v[170:173], v[38:41]
	v_mfma_f32_16x16x32_bf16 v[34:37], v[154:157], v[170:173], v[34:37]
	v_mfma_f32_16x16x32_bf16 v[22:25], v[146:149], v[178:181], v[22:25]
	v_mfma_f32_16x16x32_bf16 v[18:21], v[154:157], v[178:181], v[18:21]
	v_mfma_f32_16x16x32_bf16 v[6:9], v[146:149], v[186:189], v[6:9]
	v_mfma_f32_16x16x32_bf16 v[2:5], v[154:157], v[186:189], v[2:5]
	v_mfma_f32_16x16x32_bf16 v[54:57], v[150:153], v[166:169], v[54:57]
	v_mfma_f32_16x16x32_bf16 v[50:53], v[158:161], v[166:169], v[50:53]
	v_mfma_f32_16x16x32_bf16 v[38:41], v[150:153], v[174:177], v[38:41]
	v_mfma_f32_16x16x32_bf16 v[34:37], v[158:161], v[174:177], v[34:37]
	v_mfma_f32_16x16x32_bf16 v[22:25], v[150:153], v[182:185], v[22:25]
	v_mfma_f32_16x16x32_bf16 v[18:21], v[158:161], v[182:185], v[18:21]
	v_mfma_f32_16x16x32_bf16 v[6:9], v[150:153], v[190:193], v[6:9]
	v_mfma_f32_16x16x32_bf16 v[2:5], v[158:161], v[190:193], v[2:5]
	s_barrier
	s_setprio 0
	s_cmp_gt_u32 s36, 13
	s_cbranch_scc0 .LBB0_731
	s_and_b64 vcc, exec, s[48:49]
	s_cbranch_vccz .LBB0_734
	s_barrier
